# hand-written up_proj epilogue: conv taps via v_fmac DPP row shifts with lane-masked weights, in-place rstd scaling; plus attention B XCD remap
# speedup vs baseline: 1.0189x; 1.0189x over previous
.LBB0_1339:
	v_and_b32_e32 v56, 15, v0
	v_bfe_u32 v57, v0, 4, 2
	s_lshl_b32 s8, s12, 8
	s_add_i32 s8, s8, s63
	v_add_lshl_u32 v58, v56, s8, 2
	global_load_dword v242, v58, s[24:25]
	global_load_dword v243, v58, s[24:25] offset:64
	global_load_dword v244, v58, s[24:25] offset:128
	global_load_dword v245, v58, s[24:25] offset:192
	global_load_dword v246, v58, s[24:25] offset:512
	global_load_dword v247, v58, s[24:25] offset:576
	global_load_dword v248, v58, s[24:25] offset:640
	global_load_dword v249, v58, s[24:25] offset:704
	s_lshl_b32 s9, s13, 9
	s_lshl_b32 s22, s64, 2
	s_add_i32 s9, s9, s22
	v_lshl_add_u32 v235, v57, 5, s9
	global_load_dwordx4 v[100:103], v235, s[0:1]
	global_load_dwordx4 v[104:107], v235, s[30:31]
	global_load_dwordx4 v[112:115], v235, s[34:35]
	global_load_dwordx4 v[120:123], v235, s[2:3]
	global_load_dwordx4 v[92:95], v235, s[36:37]
	global_load_dwordx4 v[96:99], v235, s[48:49]
	global_load_dwordx4 v[108:111], v235, s[46:47]
	global_load_dwordx4 v[116:119], v235, s[44:45]
	v_cmp_lt_u32_e64 s[10:11], 13, v56
	v_cmp_gt_u32_e64 s[14:15], 2, v56
	v_cmp_eq_u32_e64 s[22:23], 0, v56
	v_lshlrev_b32_e32 v217, 8, v56
	v_lshl_add_u32 v217, v57, 5, v217
	v_add_u32_e32 v217, 0xfffff200, v217
	v_cndmask_b32_e64 v250, 0, 1.0, s[22:23]
	v_cndmask_b32_e64 v251, 0, 1.0, s[14:15]
	v_mul_u32_u24_e32 v234, 0x2c00, v56
	v_lshl_add_u32 v234, v57, 4, v234
	s_mov_b32 s41, 0xbfb8aa3b
	s_lshl_b32 s39, s12, 8
	s_add_i32 s39, s39, s63
	s_mul_i32 s39, s39, 0x2c00
	s_lshl_b32 s40, s13, 8
	s_add_i32 s39, s39, s40
	s_lshl_b32 s40, s64, 1
	s_add_i32 s39, s39, s40
	s_add_u32 s16, s70, s39
	s_addc_u32 s17, s71, 0
	s_add_u32 s18, s16, 0x160000
	s_addc_u32 s19, s17, 0
	s_waitcnt vmcnt(8)
	v_mul_f32_e32 v192, v192, v242
	v_mul_f32_e32 v193, v193, v242
	v_mul_f32_e32 v194, v194, v242
	v_mul_f32_e32 v195, v195, v242
	v_mul_f32_e32 v160, v160, v242
	v_mul_f32_e32 v161, v161, v242
	v_mul_f32_e32 v162, v162, v242
	v_mul_f32_e32 v163, v163, v242
	v_mul_f32_e32 v180, v180, v242
	v_mul_f32_e32 v181, v181, v242
	v_mul_f32_e32 v182, v182, v242
	v_mul_f32_e32 v183, v183, v242
	v_mul_f32_e32 v156, v156, v242
	v_mul_f32_e32 v157, v157, v242
	v_mul_f32_e32 v158, v158, v242
	v_mul_f32_e32 v159, v159, v242
	v_mul_f32_e32 v188, v188, v243
	v_mul_f32_e32 v189, v189, v243
	v_mul_f32_e32 v190, v190, v243
	v_mul_f32_e32 v191, v191, v243
	v_mul_f32_e32 v152, v152, v243
	v_mul_f32_e32 v153, v153, v243
	v_mul_f32_e32 v154, v154, v243
	v_mul_f32_e32 v155, v155, v243
	v_mul_f32_e32 v184, v184, v243
	v_mul_f32_e32 v185, v185, v243
	v_mul_f32_e32 v186, v186, v243
	v_mul_f32_e32 v187, v187, v243
	v_mul_f32_e32 v148, v148, v243
	v_mul_f32_e32 v149, v149, v243
	v_mul_f32_e32 v150, v150, v243
	v_mul_f32_e32 v151, v151, v243
	v_mul_f32_e32 v176, v176, v244
	v_mul_f32_e32 v177, v177, v244
	v_mul_f32_e32 v178, v178, v244
	v_mul_f32_e32 v179, v179, v244
	v_mul_f32_e32 v144, v144, v244
	v_mul_f32_e32 v145, v145, v244
	v_mul_f32_e32 v146, v146, v244
	v_mul_f32_e32 v147, v147, v244
	v_mul_f32_e32 v172, v172, v244
	v_mul_f32_e32 v173, v173, v244
	v_mul_f32_e32 v174, v174, v244
	v_mul_f32_e32 v175, v175, v244
	v_mul_f32_e32 v140, v140, v244
	v_mul_f32_e32 v141, v141, v244
	v_mul_f32_e32 v142, v142, v244
	v_mul_f32_e32 v143, v143, v244
	v_mul_f32_e32 v168, v168, v245
	v_mul_f32_e32 v169, v169, v245
	v_mul_f32_e32 v170, v170, v245
	v_mul_f32_e32 v171, v171, v245
	v_mul_f32_e32 v136, v136, v245
	v_mul_f32_e32 v137, v137, v245
	v_mul_f32_e32 v138, v138, v245
	v_mul_f32_e32 v139, v139, v245
	v_mul_f32_e32 v164, v164, v245
	v_mul_f32_e32 v165, v165, v245
	v_mul_f32_e32 v166, v166, v245
	v_mul_f32_e32 v167, v167, v245
	v_mul_f32_e32 v132, v132, v245
	v_mul_f32_e32 v133, v133, v245
	v_mul_f32_e32 v134, v134, v245
	v_mul_f32_e32 v135, v135, v245
	v_mul_f32_e32 v128, v128, v246
	v_mul_f32_e32 v129, v129, v246
	v_mul_f32_e32 v130, v130, v246
	v_mul_f32_e32 v131, v131, v246
	v_mul_f32_e32 v64, v64, v246
	v_mul_f32_e32 v65, v65, v246
	v_mul_f32_e32 v66, v66, v246
	v_mul_f32_e32 v67, v67, v246
	v_mul_f32_e32 v124, v124, v246
	v_mul_f32_e32 v125, v125, v246
	v_mul_f32_e32 v126, v126, v246
	v_mul_f32_e32 v127, v127, v246
	v_mul_f32_e32 v60, v60, v246
	v_mul_f32_e32 v61, v61, v246
	v_mul_f32_e32 v62, v62, v246
	v_mul_f32_e32 v63, v63, v246
	v_mul_f32_e32 v88, v88, v247
	v_mul_f32_e32 v89, v89, v247
	v_mul_f32_e32 v90, v90, v247
	v_mul_f32_e32 v91, v91, v247
	v_mul_f32_e32 v24, v24, v247
	v_mul_f32_e32 v25, v25, v247
	v_mul_f32_e32 v26, v26, v247
	v_mul_f32_e32 v27, v27, v247
	v_mul_f32_e32 v84, v84, v247
	v_mul_f32_e32 v85, v85, v247
	v_mul_f32_e32 v86, v86, v247
	v_mul_f32_e32 v87, v87, v247
	v_mul_f32_e32 v20, v20, v247
	v_mul_f32_e32 v21, v21, v247
	v_mul_f32_e32 v22, v22, v247
	v_mul_f32_e32 v23, v23, v247
	v_mul_f32_e32 v80, v80, v248
	v_mul_f32_e32 v81, v81, v248
	v_mul_f32_e32 v82, v82, v248
	v_mul_f32_e32 v83, v83, v248
	v_mul_f32_e32 v16, v16, v248
	v_mul_f32_e32 v17, v17, v248
	v_mul_f32_e32 v18, v18, v248
	v_mul_f32_e32 v19, v19, v248
	v_mul_f32_e32 v76, v76, v248
	v_mul_f32_e32 v77, v77, v248
	v_mul_f32_e32 v78, v78, v248
	v_mul_f32_e32 v79, v79, v248
	v_mul_f32_e32 v12, v12, v248
	v_mul_f32_e32 v13, v13, v248
	v_mul_f32_e32 v14, v14, v248
	v_mul_f32_e32 v15, v15, v248
	v_mul_f32_e32 v72, v72, v249
	v_mul_f32_e32 v73, v73, v249
	v_mul_f32_e32 v74, v74, v249
	v_mul_f32_e32 v75, v75, v249
	v_mul_f32_e32 v8, v8, v249
	v_mul_f32_e32 v9, v9, v249
	v_mul_f32_e32 v10, v10, v249
	v_mul_f32_e32 v11, v11, v249
	v_mul_f32_e32 v68, v68, v249
	v_mul_f32_e32 v69, v69, v249
	v_mul_f32_e32 v70, v70, v249
	v_mul_f32_e32 v71, v71, v249
	v_mul_f32_e32 v4, v4, v249
	v_mul_f32_e32 v5, v5, v249
	v_mul_f32_e32 v6, v6, v249
	v_mul_f32_e32 v7, v7, v249
	v_add_u32_e32 v58, s78, v217
	s_and_saveexec_b64 s[8:9], s[10:11]
	ds_write_b128 v58, v[168:171]
	ds_write_b128 v58, v[136:139] offset:16
	ds_write_b128 v58, v[164:167] offset:128
	ds_write_b128 v58, v[132:135] offset:144
	ds_write_b128 v58, v[72:75] offset:4096
	ds_write_b128 v58, v[8:11] offset:4112
	ds_write_b128 v58, v[68:71] offset:4224
	ds_write_b128 v58, v[4:7] offset:4240
	s_mov_b64 exec, s[8:9]
	s_waitcnt lgkmcnt(0)
	s_barrier
	s_waitcnt vmcnt(0)
	v_mul_f32_e32 v28, v104, v250
	v_mul_f32_e32 v29, v105, v250
	v_mul_f32_e32 v30, v106, v250
	v_mul_f32_e32 v31, v107, v250
	v_mul_f32_e32 v32, v100, v251
	v_mul_f32_e32 v33, v101, v251
	v_mul_f32_e32 v34, v102, v251
	v_mul_f32_e32 v35, v103, v251
	v_mul_f32_e32 v36, v96, v250
	v_mul_f32_e32 v37, v97, v250
	v_mul_f32_e32 v38, v98, v250
	v_mul_f32_e32 v39, v99, v250
	v_mul_f32_e32 v40, v92, v251
	v_mul_f32_e32 v41, v93, v251
	v_mul_f32_e32 v42, v94, v251
	v_mul_f32_e32 v43, v95, v251
	v_mov_b32_e32 v196, 0
	v_mov_b32_e32 v197, 0
	v_mov_b32_e32 v198, 0
	v_mov_b32_e32 v199, 0
	v_mov_b32_e32 v200, 0
	v_mov_b32_e32 v201, 0
	v_mov_b32_e32 v202, 0
	v_mov_b32_e32 v203, 0
	v_mov_b32_e32 v204, 0
	v_mov_b32_e32 v205, 0
	v_mov_b32_e32 v206, 0
	v_mov_b32_e32 v207, 0
	v_mov_b32_e32 v208, 0
	v_mov_b32_e32 v209, 0
	v_mov_b32_e32 v210, 0
	v_mov_b32_e32 v211, 0
	s_cmp_eq_u32 s63, 0
	s_cbranch_scc1 .Leu_pv0_skip_n0
	v_add_u32_e32 v58, s67, v217
	s_and_saveexec_b64 s[8:9], s[10:11]
	ds_read_b128 v[196:199], v58 offset:0
	ds_read_b128 v[200:203], v58 offset:128
	s_mov_b64 exec, s[8:9]
.Leu_pv0_skip_n0:
	s_cmp_eq_u32 s63, 0
	s_movk_i32 s40, 0x1000
	s_cselect_b32 s39, 0x800, s40
	s_add_i32 s39, s39, s67
	v_add_u32_e32 v59, s39, v217
	s_and_saveexec_b64 s[8:9], s[10:11]
	ds_read_b128 v[204:207], v59 offset:0
	ds_read_b128 v[208:211], v59 offset:128
	s_mov_b64 exec, s[8:9]
	s_waitcnt lgkmcnt(0)
	v_fma_f32 v44, v112, v192, v120
	v_fma_f32 v45, v113, v193, v121
	v_fma_f32 v46, v114, v194, v122
	v_fma_f32 v47, v115, v195, v123
	v_fma_f32 v48, v108, v180, v116
	v_fma_f32 v49, v109, v181, v117
	v_fma_f32 v50, v110, v182, v118
	v_fma_f32 v51, v111, v183, v119
	v_fmac_f32_dpp v44, v192, v104 row_shr:1 row_mask:0xf bank_mask:0xf
	v_fmac_f32_dpp v45, v193, v105 row_shr:1 row_mask:0xf bank_mask:0xf
	v_fmac_f32_dpp v46, v194, v106 row_shr:1 row_mask:0xf bank_mask:0xf
	v_fmac_f32_dpp v47, v195, v107 row_shr:1 row_mask:0xf bank_mask:0xf
	v_fmac_f32_dpp v48, v180, v96 row_shr:1 row_mask:0xf bank_mask:0xf
	v_fmac_f32_dpp v49, v181, v97 row_shr:1 row_mask:0xf bank_mask:0xf
	v_fmac_f32_dpp v50, v182, v98 row_shr:1 row_mask:0xf bank_mask:0xf
	v_fmac_f32_dpp v51, v183, v99 row_shr:1 row_mask:0xf bank_mask:0xf
	v_fmac_f32_dpp v44, v192, v100 row_shr:2 row_mask:0xf bank_mask:0xf
	v_fmac_f32_dpp v45, v193, v101 row_shr:2 row_mask:0xf bank_mask:0xf
	v_fmac_f32_dpp v46, v194, v102 row_shr:2 row_mask:0xf bank_mask:0xf
	v_fmac_f32_dpp v47, v195, v103 row_shr:2 row_mask:0xf bank_mask:0xf
	v_fmac_f32_dpp v48, v180, v92 row_shr:2 row_mask:0xf bank_mask:0xf
	v_fmac_f32_dpp v49, v181, v93 row_shr:2 row_mask:0xf bank_mask:0xf
	v_fmac_f32_dpp v50, v182, v94 row_shr:2 row_mask:0xf bank_mask:0xf
	v_fmac_f32_dpp v51, v183, v95 row_shr:2 row_mask:0xf bank_mask:0xf
	v_fmac_f32_dpp v44, v196, v28 row_ror:1 row_mask:0xf bank_mask:0xf
	v_fmac_f32_dpp v45, v197, v29 row_ror:1 row_mask:0xf bank_mask:0xf
	v_fmac_f32_dpp v46, v198, v30 row_ror:1 row_mask:0xf bank_mask:0xf
	v_fmac_f32_dpp v47, v199, v31 row_ror:1 row_mask:0xf bank_mask:0xf
	v_fmac_f32_dpp v48, v200, v36 row_ror:1 row_mask:0xf bank_mask:0xf
	v_fmac_f32_dpp v49, v201, v37 row_ror:1 row_mask:0xf bank_mask:0xf
	v_fmac_f32_dpp v50, v202, v38 row_ror:1 row_mask:0xf bank_mask:0xf
	v_fmac_f32_dpp v51, v203, v39 row_ror:1 row_mask:0xf bank_mask:0xf
	v_fmac_f32_dpp v44, v196, v32 row_ror:2 row_mask:0xf bank_mask:0xf
	v_fmac_f32_dpp v45, v197, v33 row_ror:2 row_mask:0xf bank_mask:0xf
	v_fmac_f32_dpp v46, v198, v34 row_ror:2 row_mask:0xf bank_mask:0xf
	v_fmac_f32_dpp v47, v199, v35 row_ror:2 row_mask:0xf bank_mask:0xf
	v_fmac_f32_dpp v48, v200, v40 row_ror:2 row_mask:0xf bank_mask:0xf
	v_fmac_f32_dpp v49, v201, v41 row_ror:2 row_mask:0xf bank_mask:0xf
	v_fmac_f32_dpp v50, v202, v42 row_ror:2 row_mask:0xf bank_mask:0xf
	v_fmac_f32_dpp v51, v203, v43 row_ror:2 row_mask:0xf bank_mask:0xf
	v_mul_f32_e32 v52, s41, v44
	v_mul_f32_e32 v53, s41, v45
	v_mul_f32_e32 v54, s41, v46
	v_mul_f32_e32 v55, s41, v47
	v_exp_f32_e32 v52, v52
	v_exp_f32_e32 v53, v53
	v_exp_f32_e32 v54, v54
	v_exp_f32_e32 v55, v55
	v_add_f32_e32 v52, 1.0, v52
	v_add_f32_e32 v53, 1.0, v53
	v_add_f32_e32 v54, 1.0, v54
	v_add_f32_e32 v55, 1.0, v55
	v_rcp_f32_e32 v52, v52
	v_rcp_f32_e32 v53, v53
	v_rcp_f32_e32 v54, v54
	v_rcp_f32_e32 v55, v55
	v_mul_f32_e32 v44, v44, v52
	v_mul_f32_e32 v45, v45, v53
	v_mul_f32_e32 v46, v46, v54
	v_mul_f32_e32 v47, v47, v55
	v_mul_f32_e32 v44, v48, v44
	v_mul_f32_e32 v45, v49, v45
	v_mul_f32_e32 v46, v50, v46
	v_mul_f32_e32 v47, v51, v47
	v_cvt_pk_bf16_f32 v242, v44, v45
	v_cvt_pk_bf16_f32 v243, v46, v47
	s_cmp_lg_u32 s63, 0
	s_cbranch_scc1 .Leu_halo_skip_a0n0
	v_mul_u32_u24_e32 v58, 0xb000, v56
	v_lshl_add_u32 v58, v57, 5, v58
	s_mul_i32 s39, s12, 0x2c000
	s_lshl_b32 s40, s13, 9
	s_add_i32 s39, s39, s40
	s_lshl_b32 s40, s64, 2
	s_add_i32 s39, s39, s40
	s_add_u32 s20, s72, s39
	s_addc_u32 s21, s73, 0
	s_add_u32 s22, s20, 0x5800
	s_addc_u32 s23, s21, 0
	s_and_saveexec_b64 s[8:9], s[14:15]
	global_store_dwordx4 v58, v[192:195], s[20:21]
	global_store_dwordx4 v58, v[180:183], s[22:23]
	s_mov_b64 exec, s[8:9]
.Leu_halo_skip_a0n0:
	v_fma_f32 v44, v112, v188, v120
	v_fma_f32 v45, v113, v189, v121
	v_fma_f32 v46, v114, v190, v122
	v_fma_f32 v47, v115, v191, v123
	v_fma_f32 v48, v108, v184, v116
	v_fma_f32 v49, v109, v185, v117
	v_fma_f32 v50, v110, v186, v118
	v_fma_f32 v51, v111, v187, v119
	v_fmac_f32_dpp v44, v188, v104 row_shr:1 row_mask:0xf bank_mask:0xf
	v_fmac_f32_dpp v45, v189, v105 row_shr:1 row_mask:0xf bank_mask:0xf
	v_fmac_f32_dpp v46, v190, v106 row_shr:1 row_mask:0xf bank_mask:0xf
	v_fmac_f32_dpp v47, v191, v107 row_shr:1 row_mask:0xf bank_mask:0xf
	v_fmac_f32_dpp v48, v184, v96 row_shr:1 row_mask:0xf bank_mask:0xf
	v_fmac_f32_dpp v49, v185, v97 row_shr:1 row_mask:0xf bank_mask:0xf
	v_fmac_f32_dpp v50, v186, v98 row_shr:1 row_mask:0xf bank_mask:0xf
	v_fmac_f32_dpp v51, v187, v99 row_shr:1 row_mask:0xf bank_mask:0xf
	v_fmac_f32_dpp v44, v188, v100 row_shr:2 row_mask:0xf bank_mask:0xf
	v_fmac_f32_dpp v45, v189, v101 row_shr:2 row_mask:0xf bank_mask:0xf
	v_fmac_f32_dpp v46, v190, v102 row_shr:2 row_mask:0xf bank_mask:0xf
	v_fmac_f32_dpp v47, v191, v103 row_shr:2 row_mask:0xf bank_mask:0xf
	v_fmac_f32_dpp v48, v184, v92 row_shr:2 row_mask:0xf bank_mask:0xf
	v_fmac_f32_dpp v49, v185, v93 row_shr:2 row_mask:0xf bank_mask:0xf
	v_fmac_f32_dpp v50, v186, v94 row_shr:2 row_mask:0xf bank_mask:0xf
	v_fmac_f32_dpp v51, v187, v95 row_shr:2 row_mask:0xf bank_mask:0xf
	v_fmac_f32_dpp v44, v192, v28 row_ror:1 row_mask:0xf bank_mask:0xf
	v_fmac_f32_dpp v45, v193, v29 row_ror:1 row_mask:0xf bank_mask:0xf
	v_fmac_f32_dpp v46, v194, v30 row_ror:1 row_mask:0xf bank_mask:0xf
	v_fmac_f32_dpp v47, v195, v31 row_ror:1 row_mask:0xf bank_mask:0xf
	v_fmac_f32_dpp v48, v180, v36 row_ror:1 row_mask:0xf bank_mask:0xf
	v_fmac_f32_dpp v49, v181, v37 row_ror:1 row_mask:0xf bank_mask:0xf
	v_fmac_f32_dpp v50, v182, v38 row_ror:1 row_mask:0xf bank_mask:0xf
	v_fmac_f32_dpp v51, v183, v39 row_ror:1 row_mask:0xf bank_mask:0xf
	v_fmac_f32_dpp v44, v192, v32 row_ror:2 row_mask:0xf bank_mask:0xf
	v_fmac_f32_dpp v45, v193, v33 row_ror:2 row_mask:0xf bank_mask:0xf
	v_fmac_f32_dpp v46, v194, v34 row_ror:2 row_mask:0xf bank_mask:0xf
	v_fmac_f32_dpp v47, v195, v35 row_ror:2 row_mask:0xf bank_mask:0xf
	v_fmac_f32_dpp v48, v180, v40 row_ror:2 row_mask:0xf bank_mask:0xf
	v_fmac_f32_dpp v49, v181, v41 row_ror:2 row_mask:0xf bank_mask:0xf
	v_fmac_f32_dpp v50, v182, v42 row_ror:2 row_mask:0xf bank_mask:0xf
	v_fmac_f32_dpp v51, v183, v43 row_ror:2 row_mask:0xf bank_mask:0xf
	v_mul_f32_e32 v52, s41, v44
	v_mul_f32_e32 v53, s41, v45
	v_mul_f32_e32 v54, s41, v46
	v_mul_f32_e32 v55, s41, v47
	v_exp_f32_e32 v52, v52
	v_exp_f32_e32 v53, v53
	v_exp_f32_e32 v54, v54
	v_exp_f32_e32 v55, v55
	v_add_f32_e32 v52, 1.0, v52
	v_add_f32_e32 v53, 1.0, v53
	v_add_f32_e32 v54, 1.0, v54
	v_add_f32_e32 v55, 1.0, v55
	v_rcp_f32_e32 v52, v52
	v_rcp_f32_e32 v53, v53
	v_rcp_f32_e32 v54, v54
	v_rcp_f32_e32 v55, v55
	v_mul_f32_e32 v44, v44, v52
	v_mul_f32_e32 v45, v45, v53
	v_mul_f32_e32 v46, v46, v54
	v_mul_f32_e32 v47, v47, v55
	v_mul_f32_e32 v44, v48, v44
	v_mul_f32_e32 v45, v49, v45
	v_mul_f32_e32 v46, v50, v46
	v_mul_f32_e32 v47, v51, v47
	v_cvt_pk_bf16_f32 v244, v44, v45
	v_cvt_pk_bf16_f32 v245, v46, v47
	v_fma_f32 v44, v112, v176, v120
	v_fma_f32 v45, v113, v177, v121
	v_fma_f32 v46, v114, v178, v122
	v_fma_f32 v47, v115, v179, v123
	v_fma_f32 v48, v108, v172, v116
	v_fma_f32 v49, v109, v173, v117
	v_fma_f32 v50, v110, v174, v118
	v_fma_f32 v51, v111, v175, v119
	v_fmac_f32_dpp v44, v176, v104 row_shr:1 row_mask:0xf bank_mask:0xf
	v_fmac_f32_dpp v45, v177, v105 row_shr:1 row_mask:0xf bank_mask:0xf
	v_fmac_f32_dpp v46, v178, v106 row_shr:1 row_mask:0xf bank_mask:0xf
	v_fmac_f32_dpp v47, v179, v107 row_shr:1 row_mask:0xf bank_mask:0xf
	v_fmac_f32_dpp v48, v172, v96 row_shr:1 row_mask:0xf bank_mask:0xf
	v_fmac_f32_dpp v49, v173, v97 row_shr:1 row_mask:0xf bank_mask:0xf
	v_fmac_f32_dpp v50, v174, v98 row_shr:1 row_mask:0xf bank_mask:0xf
	v_fmac_f32_dpp v51, v175, v99 row_shr:1 row_mask:0xf bank_mask:0xf
	v_fmac_f32_dpp v44, v176, v100 row_shr:2 row_mask:0xf bank_mask:0xf
	v_fmac_f32_dpp v45, v177, v101 row_shr:2 row_mask:0xf bank_mask:0xf
	v_fmac_f32_dpp v46, v178, v102 row_shr:2 row_mask:0xf bank_mask:0xf
	v_fmac_f32_dpp v47, v179, v103 row_shr:2 row_mask:0xf bank_mask:0xf
	v_fmac_f32_dpp v48, v172, v92 row_shr:2 row_mask:0xf bank_mask:0xf
	v_fmac_f32_dpp v49, v173, v93 row_shr:2 row_mask:0xf bank_mask:0xf
	v_fmac_f32_dpp v50, v174, v94 row_shr:2 row_mask:0xf bank_mask:0xf
	v_fmac_f32_dpp v51, v175, v95 row_shr:2 row_mask:0xf bank_mask:0xf
	v_fmac_f32_dpp v44, v188, v28 row_ror:1 row_mask:0xf bank_mask:0xf
	v_fmac_f32_dpp v45, v189, v29 row_ror:1 row_mask:0xf bank_mask:0xf
	v_fmac_f32_dpp v46, v190, v30 row_ror:1 row_mask:0xf bank_mask:0xf
	v_fmac_f32_dpp v47, v191, v31 row_ror:1 row_mask:0xf bank_mask:0xf
	v_fmac_f32_dpp v48, v184, v36 row_ror:1 row_mask:0xf bank_mask:0xf
	v_fmac_f32_dpp v49, v185, v37 row_ror:1 row_mask:0xf bank_mask:0xf
	v_fmac_f32_dpp v50, v186, v38 row_ror:1 row_mask:0xf bank_mask:0xf
	v_fmac_f32_dpp v51, v187, v39 row_ror:1 row_mask:0xf bank_mask:0xf
	v_fmac_f32_dpp v44, v188, v32 row_ror:2 row_mask:0xf bank_mask:0xf
	v_fmac_f32_dpp v45, v189, v33 row_ror:2 row_mask:0xf bank_mask:0xf
	v_fmac_f32_dpp v46, v190, v34 row_ror:2 row_mask:0xf bank_mask:0xf
	v_fmac_f32_dpp v47, v191, v35 row_ror:2 row_mask:0xf bank_mask:0xf
	v_fmac_f32_dpp v48, v184, v40 row_ror:2 row_mask:0xf bank_mask:0xf
	v_fmac_f32_dpp v49, v185, v41 row_ror:2 row_mask:0xf bank_mask:0xf
	v_fmac_f32_dpp v50, v186, v42 row_ror:2 row_mask:0xf bank_mask:0xf
	v_fmac_f32_dpp v51, v187, v43 row_ror:2 row_mask:0xf bank_mask:0xf
	v_mul_f32_e32 v52, s41, v44
	v_mul_f32_e32 v53, s41, v45
	v_mul_f32_e32 v54, s41, v46
	v_mul_f32_e32 v55, s41, v47
	v_exp_f32_e32 v52, v52
	v_exp_f32_e32 v53, v53
	v_exp_f32_e32 v54, v54
	v_exp_f32_e32 v55, v55
	v_add_f32_e32 v52, 1.0, v52
	v_add_f32_e32 v53, 1.0, v53
	v_add_f32_e32 v54, 1.0, v54
	v_add_f32_e32 v55, 1.0, v55
	v_rcp_f32_e32 v52, v52
	v_rcp_f32_e32 v53, v53
	v_rcp_f32_e32 v54, v54
	v_rcp_f32_e32 v55, v55
	v_mul_f32_e32 v44, v44, v52
	v_mul_f32_e32 v45, v45, v53
	v_mul_f32_e32 v46, v46, v54
	v_mul_f32_e32 v47, v47, v55
	v_mul_f32_e32 v44, v48, v44
	v_mul_f32_e32 v45, v49, v45
	v_mul_f32_e32 v46, v50, v46
	v_mul_f32_e32 v47, v51, v47
	v_cvt_pk_bf16_f32 v246, v44, v45
	v_cvt_pk_bf16_f32 v247, v46, v47
	v_fma_f32 v44, v112, v168, v120
	v_fma_f32 v45, v113, v169, v121
	v_fma_f32 v46, v114, v170, v122
	v_fma_f32 v47, v115, v171, v123
	v_fma_f32 v48, v108, v164, v116
	v_fma_f32 v49, v109, v165, v117
	v_fma_f32 v50, v110, v166, v118
	v_fma_f32 v51, v111, v167, v119
	v_fmac_f32_dpp v44, v168, v104 row_shr:1 row_mask:0xf bank_mask:0xf
	v_fmac_f32_dpp v45, v169, v105 row_shr:1 row_mask:0xf bank_mask:0xf
	v_fmac_f32_dpp v46, v170, v106 row_shr:1 row_mask:0xf bank_mask:0xf
	v_fmac_f32_dpp v47, v171, v107 row_shr:1 row_mask:0xf bank_mask:0xf
	v_fmac_f32_dpp v48, v164, v96 row_shr:1 row_mask:0xf bank_mask:0xf
	v_fmac_f32_dpp v49, v165, v97 row_shr:1 row_mask:0xf bank_mask:0xf
	v_fmac_f32_dpp v50, v166, v98 row_shr:1 row_mask:0xf bank_mask:0xf
	v_fmac_f32_dpp v51, v167, v99 row_shr:1 row_mask:0xf bank_mask:0xf
	v_fmac_f32_dpp v44, v168, v100 row_shr:2 row_mask:0xf bank_mask:0xf
	v_fmac_f32_dpp v45, v169, v101 row_shr:2 row_mask:0xf bank_mask:0xf
	v_fmac_f32_dpp v46, v170, v102 row_shr:2 row_mask:0xf bank_mask:0xf
	v_fmac_f32_dpp v47, v171, v103 row_shr:2 row_mask:0xf bank_mask:0xf
	v_fmac_f32_dpp v48, v164, v92 row_shr:2 row_mask:0xf bank_mask:0xf
	v_fmac_f32_dpp v49, v165, v93 row_shr:2 row_mask:0xf bank_mask:0xf
	v_fmac_f32_dpp v50, v166, v94 row_shr:2 row_mask:0xf bank_mask:0xf
	v_fmac_f32_dpp v51, v167, v95 row_shr:2 row_mask:0xf bank_mask:0xf
	v_fmac_f32_dpp v44, v176, v28 row_ror:1 row_mask:0xf bank_mask:0xf
	v_fmac_f32_dpp v45, v177, v29 row_ror:1 row_mask:0xf bank_mask:0xf
	v_fmac_f32_dpp v46, v178, v30 row_ror:1 row_mask:0xf bank_mask:0xf
	v_fmac_f32_dpp v47, v179, v31 row_ror:1 row_mask:0xf bank_mask:0xf
	v_fmac_f32_dpp v48, v172, v36 row_ror:1 row_mask:0xf bank_mask:0xf
	v_fmac_f32_dpp v49, v173, v37 row_ror:1 row_mask:0xf bank_mask:0xf
	v_fmac_f32_dpp v50, v174, v38 row_ror:1 row_mask:0xf bank_mask:0xf
	v_fmac_f32_dpp v51, v175, v39 row_ror:1 row_mask:0xf bank_mask:0xf
	v_fmac_f32_dpp v44, v176, v32 row_ror:2 row_mask:0xf bank_mask:0xf
	v_fmac_f32_dpp v45, v177, v33 row_ror:2 row_mask:0xf bank_mask:0xf
	v_fmac_f32_dpp v46, v178, v34 row_ror:2 row_mask:0xf bank_mask:0xf
	v_fmac_f32_dpp v47, v179, v35 row_ror:2 row_mask:0xf bank_mask:0xf
	v_fmac_f32_dpp v48, v172, v40 row_ror:2 row_mask:0xf bank_mask:0xf
	v_fmac_f32_dpp v49, v173, v41 row_ror:2 row_mask:0xf bank_mask:0xf
	v_fmac_f32_dpp v50, v174, v42 row_ror:2 row_mask:0xf bank_mask:0xf
	v_fmac_f32_dpp v51, v175, v43 row_ror:2 row_mask:0xf bank_mask:0xf
	v_mul_f32_e32 v52, s41, v44
	v_mul_f32_e32 v53, s41, v45
	v_mul_f32_e32 v54, s41, v46
	v_mul_f32_e32 v55, s41, v47
	v_exp_f32_e32 v52, v52
	v_exp_f32_e32 v53, v53
	v_exp_f32_e32 v54, v54
	v_exp_f32_e32 v55, v55
	v_add_f32_e32 v52, 1.0, v52
	v_add_f32_e32 v53, 1.0, v53
	v_add_f32_e32 v54, 1.0, v54
	v_add_f32_e32 v55, 1.0, v55
	v_rcp_f32_e32 v52, v52
	v_rcp_f32_e32 v53, v53
	v_rcp_f32_e32 v54, v54
	v_rcp_f32_e32 v55, v55
	v_mul_f32_e32 v44, v44, v52
	v_mul_f32_e32 v45, v45, v53
	v_mul_f32_e32 v46, v46, v54
	v_mul_f32_e32 v47, v47, v55
	v_mul_f32_e32 v44, v48, v44
	v_mul_f32_e32 v45, v49, v45
	v_mul_f32_e32 v46, v50, v46
	v_mul_f32_e32 v47, v51, v47
	v_cvt_pk_bf16_f32 v248, v44, v45
	v_cvt_pk_bf16_f32 v249, v46, v47
	global_load_dwordx4 v[236:239], v235, s[0:1] offset:16
	global_load_dwordx4 v[192:195], v235, s[30:31] offset:16
	global_load_dwordx4 v[180:183], v235, s[34:35] offset:16
	global_load_dwordx4 v[188:191], v235, s[2:3] offset:16
	global_load_dwordx4 v[184:187], v235, s[36:37] offset:16
	global_load_dwordx4 v[176:179], v235, s[48:49] offset:16
	global_load_dwordx4 v[172:175], v235, s[46:47] offset:16
	global_load_dwordx4 v[168:171], v235, s[44:45] offset:16
	v_fma_f32 v44, v112, v128, v120
	v_fma_f32 v45, v113, v129, v121
	v_fma_f32 v46, v114, v130, v122
	v_fma_f32 v47, v115, v131, v123
	v_fma_f32 v48, v108, v124, v116
	v_fma_f32 v49, v109, v125, v117
	v_fma_f32 v50, v110, v126, v118
	v_fma_f32 v51, v111, v127, v119
	v_fmac_f32_dpp v44, v128, v104 row_shr:1 row_mask:0xf bank_mask:0xf
	v_fmac_f32_dpp v45, v129, v105 row_shr:1 row_mask:0xf bank_mask:0xf
	v_fmac_f32_dpp v46, v130, v106 row_shr:1 row_mask:0xf bank_mask:0xf
	v_fmac_f32_dpp v47, v131, v107 row_shr:1 row_mask:0xf bank_mask:0xf
	v_fmac_f32_dpp v48, v124, v96 row_shr:1 row_mask:0xf bank_mask:0xf
	v_fmac_f32_dpp v49, v125, v97 row_shr:1 row_mask:0xf bank_mask:0xf
	v_fmac_f32_dpp v50, v126, v98 row_shr:1 row_mask:0xf bank_mask:0xf
	v_fmac_f32_dpp v51, v127, v99 row_shr:1 row_mask:0xf bank_mask:0xf
	v_fmac_f32_dpp v44, v128, v100 row_shr:2 row_mask:0xf bank_mask:0xf
	v_fmac_f32_dpp v45, v129, v101 row_shr:2 row_mask:0xf bank_mask:0xf
	v_fmac_f32_dpp v46, v130, v102 row_shr:2 row_mask:0xf bank_mask:0xf
	v_fmac_f32_dpp v47, v131, v103 row_shr:2 row_mask:0xf bank_mask:0xf
	v_fmac_f32_dpp v48, v124, v92 row_shr:2 row_mask:0xf bank_mask:0xf
	v_fmac_f32_dpp v49, v125, v93 row_shr:2 row_mask:0xf bank_mask:0xf
	v_fmac_f32_dpp v50, v126, v94 row_shr:2 row_mask:0xf bank_mask:0xf
	v_fmac_f32_dpp v51, v127, v95 row_shr:2 row_mask:0xf bank_mask:0xf
	v_fmac_f32_dpp v44, v204, v28 row_ror:1 row_mask:0xf bank_mask:0xf
	v_fmac_f32_dpp v45, v205, v29 row_ror:1 row_mask:0xf bank_mask:0xf
	v_fmac_f32_dpp v46, v206, v30 row_ror:1 row_mask:0xf bank_mask:0xf
	v_fmac_f32_dpp v47, v207, v31 row_ror:1 row_mask:0xf bank_mask:0xf
	v_fmac_f32_dpp v48, v208, v36 row_ror:1 row_mask:0xf bank_mask:0xf
	v_fmac_f32_dpp v49, v209, v37 row_ror:1 row_mask:0xf bank_mask:0xf
	v_fmac_f32_dpp v50, v210, v38 row_ror:1 row_mask:0xf bank_mask:0xf
	v_fmac_f32_dpp v51, v211, v39 row_ror:1 row_mask:0xf bank_mask:0xf
	v_fmac_f32_dpp v44, v204, v32 row_ror:2 row_mask:0xf bank_mask:0xf
	v_fmac_f32_dpp v45, v205, v33 row_ror:2 row_mask:0xf bank_mask:0xf
	v_fmac_f32_dpp v46, v206, v34 row_ror:2 row_mask:0xf bank_mask:0xf
	v_fmac_f32_dpp v47, v207, v35 row_ror:2 row_mask:0xf bank_mask:0xf
	v_fmac_f32_dpp v48, v208, v40 row_ror:2 row_mask:0xf bank_mask:0xf
	v_fmac_f32_dpp v49, v209, v41 row_ror:2 row_mask:0xf bank_mask:0xf
	v_fmac_f32_dpp v50, v210, v42 row_ror:2 row_mask:0xf bank_mask:0xf
	v_fmac_f32_dpp v51, v211, v43 row_ror:2 row_mask:0xf bank_mask:0xf
	v_mul_f32_e32 v52, s41, v44
	v_mul_f32_e32 v53, s41, v45
	v_mul_f32_e32 v54, s41, v46
	v_mul_f32_e32 v55, s41, v47
	v_exp_f32_e32 v52, v52
	v_exp_f32_e32 v53, v53
	v_exp_f32_e32 v54, v54
	v_exp_f32_e32 v55, v55
	v_add_f32_e32 v52, 1.0, v52
	v_add_f32_e32 v53, 1.0, v53
	v_add_f32_e32 v54, 1.0, v54
	v_add_f32_e32 v55, 1.0, v55
	v_rcp_f32_e32 v52, v52
	v_rcp_f32_e32 v53, v53
	v_rcp_f32_e32 v54, v54
	v_rcp_f32_e32 v55, v55
	v_mul_f32_e32 v44, v44, v52
	v_mul_f32_e32 v45, v45, v53
	v_mul_f32_e32 v46, v46, v54
	v_mul_f32_e32 v47, v47, v55
	v_mul_f32_e32 v44, v48, v44
	v_mul_f32_e32 v45, v49, v45
	v_mul_f32_e32 v46, v50, v46
	v_mul_f32_e32 v47, v51, v47
	v_cvt_pk_bf16_f32 v164, v44, v45
	v_cvt_pk_bf16_f32 v165, v46, v47
	v_fma_f32 v44, v112, v88, v120
	v_fma_f32 v45, v113, v89, v121
	v_fma_f32 v46, v114, v90, v122
	v_fma_f32 v47, v115, v91, v123
	v_fma_f32 v48, v108, v84, v116
	v_fma_f32 v49, v109, v85, v117
	v_fma_f32 v50, v110, v86, v118
	v_fma_f32 v51, v111, v87, v119
	v_fmac_f32_dpp v44, v88, v104 row_shr:1 row_mask:0xf bank_mask:0xf
	v_fmac_f32_dpp v45, v89, v105 row_shr:1 row_mask:0xf bank_mask:0xf
	v_fmac_f32_dpp v46, v90, v106 row_shr:1 row_mask:0xf bank_mask:0xf
	v_fmac_f32_dpp v47, v91, v107 row_shr:1 row_mask:0xf bank_mask:0xf
	v_fmac_f32_dpp v48, v84, v96 row_shr:1 row_mask:0xf bank_mask:0xf
	v_fmac_f32_dpp v49, v85, v97 row_shr:1 row_mask:0xf bank_mask:0xf
	v_fmac_f32_dpp v50, v86, v98 row_shr:1 row_mask:0xf bank_mask:0xf
	v_fmac_f32_dpp v51, v87, v99 row_shr:1 row_mask:0xf bank_mask:0xf
	v_fmac_f32_dpp v44, v88, v100 row_shr:2 row_mask:0xf bank_mask:0xf
	v_fmac_f32_dpp v45, v89, v101 row_shr:2 row_mask:0xf bank_mask:0xf
	v_fmac_f32_dpp v46, v90, v102 row_shr:2 row_mask:0xf bank_mask:0xf
	v_fmac_f32_dpp v47, v91, v103 row_shr:2 row_mask:0xf bank_mask:0xf
	v_fmac_f32_dpp v48, v84, v92 row_shr:2 row_mask:0xf bank_mask:0xf
	v_fmac_f32_dpp v49, v85, v93 row_shr:2 row_mask:0xf bank_mask:0xf
	v_fmac_f32_dpp v50, v86, v94 row_shr:2 row_mask:0xf bank_mask:0xf
	v_fmac_f32_dpp v51, v87, v95 row_shr:2 row_mask:0xf bank_mask:0xf
	v_fmac_f32_dpp v44, v128, v28 row_ror:1 row_mask:0xf bank_mask:0xf
	v_fmac_f32_dpp v45, v129, v29 row_ror:1 row_mask:0xf bank_mask:0xf
	v_fmac_f32_dpp v46, v130, v30 row_ror:1 row_mask:0xf bank_mask:0xf
	v_fmac_f32_dpp v47, v131, v31 row_ror:1 row_mask:0xf bank_mask:0xf
	v_fmac_f32_dpp v48, v124, v36 row_ror:1 row_mask:0xf bank_mask:0xf
	v_fmac_f32_dpp v49, v125, v37 row_ror:1 row_mask:0xf bank_mask:0xf
	v_fmac_f32_dpp v50, v126, v38 row_ror:1 row_mask:0xf bank_mask:0xf
	v_fmac_f32_dpp v51, v127, v39 row_ror:1 row_mask:0xf bank_mask:0xf
	v_fmac_f32_dpp v44, v128, v32 row_ror:2 row_mask:0xf bank_mask:0xf
	v_fmac_f32_dpp v45, v129, v33 row_ror:2 row_mask:0xf bank_mask:0xf
	v_fmac_f32_dpp v46, v130, v34 row_ror:2 row_mask:0xf bank_mask:0xf
	v_fmac_f32_dpp v47, v131, v35 row_ror:2 row_mask:0xf bank_mask:0xf
	v_fmac_f32_dpp v48, v124, v40 row_ror:2 row_mask:0xf bank_mask:0xf
	v_fmac_f32_dpp v49, v125, v41 row_ror:2 row_mask:0xf bank_mask:0xf
	v_fmac_f32_dpp v50, v126, v42 row_ror:2 row_mask:0xf bank_mask:0xf
	v_fmac_f32_dpp v51, v127, v43 row_ror:2 row_mask:0xf bank_mask:0xf
	v_mul_f32_e32 v52, s41, v44
	v_mul_f32_e32 v53, s41, v45
	v_mul_f32_e32 v54, s41, v46
	v_mul_f32_e32 v55, s41, v47
	v_exp_f32_e32 v52, v52
	v_exp_f32_e32 v53, v53
	v_exp_f32_e32 v54, v54
	v_exp_f32_e32 v55, v55
	v_add_f32_e32 v52, 1.0, v52
	v_add_f32_e32 v53, 1.0, v53
	v_add_f32_e32 v54, 1.0, v54
	v_add_f32_e32 v55, 1.0, v55
	v_rcp_f32_e32 v52, v52
	v_rcp_f32_e32 v53, v53
	v_rcp_f32_e32 v54, v54
	v_rcp_f32_e32 v55, v55
	v_mul_f32_e32 v44, v44, v52
	v_mul_f32_e32 v45, v45, v53
	v_mul_f32_e32 v46, v46, v54
	v_mul_f32_e32 v47, v47, v55
	v_mul_f32_e32 v44, v48, v44
	v_mul_f32_e32 v45, v49, v45
	v_mul_f32_e32 v46, v50, v46
	v_mul_f32_e32 v47, v51, v47
	v_cvt_pk_bf16_f32 v166, v44, v45
	v_cvt_pk_bf16_f32 v167, v46, v47
	v_fma_f32 v44, v112, v80, v120
	v_fma_f32 v45, v113, v81, v121
	v_fma_f32 v46, v114, v82, v122
	v_fma_f32 v47, v115, v83, v123
	v_fma_f32 v48, v108, v76, v116
	v_fma_f32 v49, v109, v77, v117
	v_fma_f32 v50, v110, v78, v118
	v_fma_f32 v51, v111, v79, v119
	v_fmac_f32_dpp v44, v80, v104 row_shr:1 row_mask:0xf bank_mask:0xf
	v_fmac_f32_dpp v45, v81, v105 row_shr:1 row_mask:0xf bank_mask:0xf
	v_fmac_f32_dpp v46, v82, v106 row_shr:1 row_mask:0xf bank_mask:0xf
	v_fmac_f32_dpp v47, v83, v107 row_shr:1 row_mask:0xf bank_mask:0xf
	v_fmac_f32_dpp v48, v76, v96 row_shr:1 row_mask:0xf bank_mask:0xf
	v_fmac_f32_dpp v49, v77, v97 row_shr:1 row_mask:0xf bank_mask:0xf
	v_fmac_f32_dpp v50, v78, v98 row_shr:1 row_mask:0xf bank_mask:0xf
	v_fmac_f32_dpp v51, v79, v99 row_shr:1 row_mask:0xf bank_mask:0xf
	v_fmac_f32_dpp v44, v80, v100 row_shr:2 row_mask:0xf bank_mask:0xf
	v_fmac_f32_dpp v45, v81, v101 row_shr:2 row_mask:0xf bank_mask:0xf
	v_fmac_f32_dpp v46, v82, v102 row_shr:2 row_mask:0xf bank_mask:0xf
	v_fmac_f32_dpp v47, v83, v103 row_shr:2 row_mask:0xf bank_mask:0xf
	v_fmac_f32_dpp v48, v76, v92 row_shr:2 row_mask:0xf bank_mask:0xf
	v_fmac_f32_dpp v49, v77, v93 row_shr:2 row_mask:0xf bank_mask:0xf
	v_fmac_f32_dpp v50, v78, v94 row_shr:2 row_mask:0xf bank_mask:0xf
	v_fmac_f32_dpp v51, v79, v95 row_shr:2 row_mask:0xf bank_mask:0xf
	v_fmac_f32_dpp v44, v88, v28 row_ror:1 row_mask:0xf bank_mask:0xf
	v_fmac_f32_dpp v45, v89, v29 row_ror:1 row_mask:0xf bank_mask:0xf
	v_fmac_f32_dpp v46, v90, v30 row_ror:1 row_mask:0xf bank_mask:0xf
	v_fmac_f32_dpp v47, v91, v31 row_ror:1 row_mask:0xf bank_mask:0xf
	v_fmac_f32_dpp v48, v84, v36 row_ror:1 row_mask:0xf bank_mask:0xf
	v_fmac_f32_dpp v49, v85, v37 row_ror:1 row_mask:0xf bank_mask:0xf
	v_fmac_f32_dpp v50, v86, v38 row_ror:1 row_mask:0xf bank_mask:0xf
	v_fmac_f32_dpp v51, v87, v39 row_ror:1 row_mask:0xf bank_mask:0xf
	v_fmac_f32_dpp v44, v88, v32 row_ror:2 row_mask:0xf bank_mask:0xf
	v_fmac_f32_dpp v45, v89, v33 row_ror:2 row_mask:0xf bank_mask:0xf
	v_fmac_f32_dpp v46, v90, v34 row_ror:2 row_mask:0xf bank_mask:0xf
	v_fmac_f32_dpp v47, v91, v35 row_ror:2 row_mask:0xf bank_mask:0xf
	v_fmac_f32_dpp v48, v84, v40 row_ror:2 row_mask:0xf bank_mask:0xf
	v_fmac_f32_dpp v49, v85, v41 row_ror:2 row_mask:0xf bank_mask:0xf
	v_fmac_f32_dpp v50, v86, v42 row_ror:2 row_mask:0xf bank_mask:0xf
	v_fmac_f32_dpp v51, v87, v43 row_ror:2 row_mask:0xf bank_mask:0xf
	v_mul_f32_e32 v52, s41, v44
	v_mul_f32_e32 v53, s41, v45
	v_mul_f32_e32 v54, s41, v46
	v_mul_f32_e32 v55, s41, v47
	v_exp_f32_e32 v52, v52
	v_exp_f32_e32 v53, v53
	v_exp_f32_e32 v54, v54
	v_exp_f32_e32 v55, v55
	v_add_f32_e32 v52, 1.0, v52
	v_add_f32_e32 v53, 1.0, v53
	v_add_f32_e32 v54, 1.0, v54
	v_add_f32_e32 v55, 1.0, v55
	v_rcp_f32_e32 v52, v52
	v_rcp_f32_e32 v53, v53
	v_rcp_f32_e32 v54, v54
	v_rcp_f32_e32 v55, v55
	v_mul_f32_e32 v44, v44, v52
	v_mul_f32_e32 v45, v45, v53
	v_mul_f32_e32 v46, v46, v54
	v_mul_f32_e32 v47, v47, v55
	v_mul_f32_e32 v44, v48, v44
	v_mul_f32_e32 v45, v49, v45
	v_mul_f32_e32 v46, v50, v46
	v_mul_f32_e32 v47, v51, v47
	v_cvt_pk_bf16_f32 v128, v44, v45
	v_cvt_pk_bf16_f32 v129, v46, v47
	v_fma_f32 v44, v112, v72, v120
	v_fma_f32 v45, v113, v73, v121
	v_fma_f32 v46, v114, v74, v122
	v_fma_f32 v47, v115, v75, v123
	v_fma_f32 v48, v108, v68, v116
	v_fma_f32 v49, v109, v69, v117
	v_fma_f32 v50, v110, v70, v118
	v_fma_f32 v51, v111, v71, v119
	v_fmac_f32_dpp v44, v72, v104 row_shr:1 row_mask:0xf bank_mask:0xf
	v_fmac_f32_dpp v45, v73, v105 row_shr:1 row_mask:0xf bank_mask:0xf
	v_fmac_f32_dpp v46, v74, v106 row_shr:1 row_mask:0xf bank_mask:0xf
	v_fmac_f32_dpp v47, v75, v107 row_shr:1 row_mask:0xf bank_mask:0xf
	v_fmac_f32_dpp v48, v68, v96 row_shr:1 row_mask:0xf bank_mask:0xf
	v_fmac_f32_dpp v49, v69, v97 row_shr:1 row_mask:0xf bank_mask:0xf
	v_fmac_f32_dpp v50, v70, v98 row_shr:1 row_mask:0xf bank_mask:0xf
	v_fmac_f32_dpp v51, v71, v99 row_shr:1 row_mask:0xf bank_mask:0xf
	v_fmac_f32_dpp v44, v72, v100 row_shr:2 row_mask:0xf bank_mask:0xf
	v_fmac_f32_dpp v45, v73, v101 row_shr:2 row_mask:0xf bank_mask:0xf
	v_fmac_f32_dpp v46, v74, v102 row_shr:2 row_mask:0xf bank_mask:0xf
	v_fmac_f32_dpp v47, v75, v103 row_shr:2 row_mask:0xf bank_mask:0xf
	v_fmac_f32_dpp v48, v68, v92 row_shr:2 row_mask:0xf bank_mask:0xf
	v_fmac_f32_dpp v49, v69, v93 row_shr:2 row_mask:0xf bank_mask:0xf
	v_fmac_f32_dpp v50, v70, v94 row_shr:2 row_mask:0xf bank_mask:0xf
	v_fmac_f32_dpp v51, v71, v95 row_shr:2 row_mask:0xf bank_mask:0xf
	v_fmac_f32_dpp v44, v80, v28 row_ror:1 row_mask:0xf bank_mask:0xf
	v_fmac_f32_dpp v45, v81, v29 row_ror:1 row_mask:0xf bank_mask:0xf
	v_fmac_f32_dpp v46, v82, v30 row_ror:1 row_mask:0xf bank_mask:0xf
	v_fmac_f32_dpp v47, v83, v31 row_ror:1 row_mask:0xf bank_mask:0xf
	v_fmac_f32_dpp v48, v76, v36 row_ror:1 row_mask:0xf bank_mask:0xf
	v_fmac_f32_dpp v49, v77, v37 row_ror:1 row_mask:0xf bank_mask:0xf
	v_fmac_f32_dpp v50, v78, v38 row_ror:1 row_mask:0xf bank_mask:0xf
	v_fmac_f32_dpp v51, v79, v39 row_ror:1 row_mask:0xf bank_mask:0xf
	v_fmac_f32_dpp v44, v80, v32 row_ror:2 row_mask:0xf bank_mask:0xf
	v_fmac_f32_dpp v45, v81, v33 row_ror:2 row_mask:0xf bank_mask:0xf
	v_fmac_f32_dpp v46, v82, v34 row_ror:2 row_mask:0xf bank_mask:0xf
	v_fmac_f32_dpp v47, v83, v35 row_ror:2 row_mask:0xf bank_mask:0xf
	v_fmac_f32_dpp v48, v76, v40 row_ror:2 row_mask:0xf bank_mask:0xf
	v_fmac_f32_dpp v49, v77, v41 row_ror:2 row_mask:0xf bank_mask:0xf
	v_fmac_f32_dpp v50, v78, v42 row_ror:2 row_mask:0xf bank_mask:0xf
	v_fmac_f32_dpp v51, v79, v43 row_ror:2 row_mask:0xf bank_mask:0xf
	v_mul_f32_e32 v52, s41, v44
	v_mul_f32_e32 v53, s41, v45
	v_mul_f32_e32 v54, s41, v46
	v_mul_f32_e32 v55, s41, v47
	v_exp_f32_e32 v52, v52
	v_exp_f32_e32 v53, v53
	v_exp_f32_e32 v54, v54
	v_exp_f32_e32 v55, v55
	v_add_f32_e32 v52, 1.0, v52
	v_add_f32_e32 v53, 1.0, v53
	v_add_f32_e32 v54, 1.0, v54
	v_add_f32_e32 v55, 1.0, v55
	v_rcp_f32_e32 v52, v52
	v_rcp_f32_e32 v53, v53
	v_rcp_f32_e32 v54, v54
	v_rcp_f32_e32 v55, v55
	v_mul_f32_e32 v44, v44, v52
	v_mul_f32_e32 v45, v45, v53
	v_mul_f32_e32 v46, v46, v54
	v_mul_f32_e32 v47, v47, v55
	v_mul_f32_e32 v44, v48, v44
	v_mul_f32_e32 v45, v49, v45
	v_mul_f32_e32 v46, v50, v46
	v_mul_f32_e32 v47, v51, v47
	v_cvt_pk_bf16_f32 v130, v44, v45
	v_cvt_pk_bf16_f32 v131, v46, v47
	s_cmp_eq_u32 s63, 0
	s_cbranch_scc1 .Leu_halo_skip_a1n0
	v_subrev_u32_e32 v58, 12, v56
	v_mul_u32_u24_e32 v58, 0xb000, v58
	v_lshl_add_u32 v58, v57, 5, v58
	s_mul_i32 s39, s12, 0x2c000
	s_lshl_b32 s40, s13, 9
	s_add_i32 s39, s39, s40
	s_lshl_b32 s40, s64, 2
	s_add_i32 s39, s39, s40
	s_add_u32 s20, s72, s39
	s_addc_u32 s21, s73, 0
	s_add_u32 s22, s20, 0x5800
	s_addc_u32 s23, s21, 0
	s_and_saveexec_b64 s[8:9], s[10:11]
	global_store_dwordx4 v58, v[72:75], s[20:21]
	global_store_dwordx4 v58, v[68:71], s[22:23]
	s_and_b32 s39, s12, 7
	s_cmp_lg_u32 s39, 7
	s_cbranch_scc1 .Leu_ffn_skip_a1n0
	v_subrev_u32_e32 v59, 14, v56
	v_mul_u32_u24_e32 v59, 0xb000, v59
	v_lshl_add_u32 v59, v57, 5, v59
	s_lshr_b32 s39, s12, 3
	s_mul_i32 s39, s39, 0x16000
	s_lshl_b32 s40, s13, 9
	s_add_i32 s39, s39, s40
	s_lshl_b32 s40, s64, 2
	s_add_i32 s39, s39, s40
	s_add_u32 s20, s28, s39
	s_addc_u32 s21, s29, 0
	s_add_u32 s22, s20, 0x5800
	s_addc_u32 s23, s21, 0
	global_store_dwordx4 v59, v[72:75], s[20:21]
	global_store_dwordx4 v59, v[68:71], s[22:23]
.Leu_ffn_skip_a1n0:
	s_mov_b64 exec, s[8:9]
.Leu_halo_skip_a1n0:
	v_mov_b32_e32 v196, 0
	v_mov_b32_e32 v197, 0
	v_mov_b32_e32 v198, 0
	v_mov_b32_e32 v199, 0
	v_mov_b32_e32 v200, 0
	v_mov_b32_e32 v201, 0
	v_mov_b32_e32 v202, 0
	v_mov_b32_e32 v203, 0
	v_mov_b32_e32 v204, 0
	v_mov_b32_e32 v205, 0
	v_mov_b32_e32 v206, 0
	v_mov_b32_e32 v207, 0
	v_mov_b32_e32 v208, 0
	v_mov_b32_e32 v209, 0
	v_mov_b32_e32 v210, 0
	v_mov_b32_e32 v211, 0
	s_cmp_eq_u32 s63, 0
	s_cbranch_scc1 .Leu_pv0_skip_n1
	v_add_u32_e32 v58, s67, v217
	s_and_saveexec_b64 s[8:9], s[10:11]
	ds_read_b128 v[196:199], v58 offset:16
	ds_read_b128 v[200:203], v58 offset:144
	s_mov_b64 exec, s[8:9]
.Leu_pv0_skip_n1:
	s_cmp_eq_u32 s63, 0
	s_movk_i32 s40, 0x1000
	s_cselect_b32 s39, 0x800, s40
	s_add_i32 s39, s39, s67
	v_add_u32_e32 v59, s39, v217
	s_and_saveexec_b64 s[8:9], s[10:11]
	ds_read_b128 v[204:207], v59 offset:16
	ds_read_b128 v[208:211], v59 offset:144
	s_mov_b64 exec, s[8:9]
	s_waitcnt vmcnt(0) lgkmcnt(0)
	v_mul_f32_e32 v28, v192, v250
	v_mul_f32_e32 v29, v193, v250
	v_mul_f32_e32 v30, v194, v250
	v_mul_f32_e32 v31, v195, v250
	v_mul_f32_e32 v32, v236, v251
	v_mul_f32_e32 v33, v237, v251
	v_mul_f32_e32 v34, v238, v251
	v_mul_f32_e32 v35, v239, v251
	v_mul_f32_e32 v36, v176, v250
	v_mul_f32_e32 v37, v177, v250
	v_mul_f32_e32 v38, v178, v250
	v_mul_f32_e32 v39, v179, v250
	v_mul_f32_e32 v40, v184, v251
	v_mul_f32_e32 v41, v185, v251
	v_mul_f32_e32 v42, v186, v251
	v_mul_f32_e32 v43, v187, v251
	v_fma_f32 v44, v180, v160, v188
	v_fma_f32 v45, v181, v161, v189
	v_fma_f32 v46, v182, v162, v190
	v_fma_f32 v47, v183, v163, v191
	v_fma_f32 v48, v172, v156, v168
	v_fma_f32 v49, v173, v157, v169
	v_fma_f32 v50, v174, v158, v170
	v_fma_f32 v51, v175, v159, v171
	v_fmac_f32_dpp v44, v160, v192 row_shr:1 row_mask:0xf bank_mask:0xf
	v_fmac_f32_dpp v45, v161, v193 row_shr:1 row_mask:0xf bank_mask:0xf
	v_fmac_f32_dpp v46, v162, v194 row_shr:1 row_mask:0xf bank_mask:0xf
	v_fmac_f32_dpp v47, v163, v195 row_shr:1 row_mask:0xf bank_mask:0xf
	v_fmac_f32_dpp v48, v156, v176 row_shr:1 row_mask:0xf bank_mask:0xf
	v_fmac_f32_dpp v49, v157, v177 row_shr:1 row_mask:0xf bank_mask:0xf
	v_fmac_f32_dpp v50, v158, v178 row_shr:1 row_mask:0xf bank_mask:0xf
	v_fmac_f32_dpp v51, v159, v179 row_shr:1 row_mask:0xf bank_mask:0xf
	v_fmac_f32_dpp v44, v160, v236 row_shr:2 row_mask:0xf bank_mask:0xf
	v_fmac_f32_dpp v45, v161, v237 row_shr:2 row_mask:0xf bank_mask:0xf
	v_fmac_f32_dpp v46, v162, v238 row_shr:2 row_mask:0xf bank_mask:0xf
	v_fmac_f32_dpp v47, v163, v239 row_shr:2 row_mask:0xf bank_mask:0xf
	v_fmac_f32_dpp v48, v156, v184 row_shr:2 row_mask:0xf bank_mask:0xf
	v_fmac_f32_dpp v49, v157, v185 row_shr:2 row_mask:0xf bank_mask:0xf
	v_fmac_f32_dpp v50, v158, v186 row_shr:2 row_mask:0xf bank_mask:0xf
	v_fmac_f32_dpp v51, v159, v187 row_shr:2 row_mask:0xf bank_mask:0xf
	v_fmac_f32_dpp v44, v196, v28 row_ror:1 row_mask:0xf bank_mask:0xf
	v_fmac_f32_dpp v45, v197, v29 row_ror:1 row_mask:0xf bank_mask:0xf
	v_fmac_f32_dpp v46, v198, v30 row_ror:1 row_mask:0xf bank_mask:0xf
	v_fmac_f32_dpp v47, v199, v31 row_ror:1 row_mask:0xf bank_mask:0xf
	v_fmac_f32_dpp v48, v200, v36 row_ror:1 row_mask:0xf bank_mask:0xf
	v_fmac_f32_dpp v49, v201, v37 row_ror:1 row_mask:0xf bank_mask:0xf
	v_fmac_f32_dpp v50, v202, v38 row_ror:1 row_mask:0xf bank_mask:0xf
	v_fmac_f32_dpp v51, v203, v39 row_ror:1 row_mask:0xf bank_mask:0xf
	v_fmac_f32_dpp v44, v196, v32 row_ror:2 row_mask:0xf bank_mask:0xf
	v_fmac_f32_dpp v45, v197, v33 row_ror:2 row_mask:0xf bank_mask:0xf
	v_fmac_f32_dpp v46, v198, v34 row_ror:2 row_mask:0xf bank_mask:0xf
	v_fmac_f32_dpp v47, v199, v35 row_ror:2 row_mask:0xf bank_mask:0xf
	v_fmac_f32_dpp v48, v200, v40 row_ror:2 row_mask:0xf bank_mask:0xf
	v_fmac_f32_dpp v49, v201, v41 row_ror:2 row_mask:0xf bank_mask:0xf
	v_fmac_f32_dpp v50, v202, v42 row_ror:2 row_mask:0xf bank_mask:0xf
	v_fmac_f32_dpp v51, v203, v43 row_ror:2 row_mask:0xf bank_mask:0xf
	v_mul_f32_e32 v52, s41, v44
	v_mul_f32_e32 v53, s41, v45
	v_mul_f32_e32 v54, s41, v46
	v_mul_f32_e32 v55, s41, v47
	v_exp_f32_e32 v52, v52
	v_exp_f32_e32 v53, v53
	v_exp_f32_e32 v54, v54
	v_exp_f32_e32 v55, v55
	v_add_f32_e32 v52, 1.0, v52
	v_add_f32_e32 v53, 1.0, v53
	v_add_f32_e32 v54, 1.0, v54
	v_add_f32_e32 v55, 1.0, v55
	v_rcp_f32_e32 v52, v52
	v_rcp_f32_e32 v53, v53
	v_rcp_f32_e32 v54, v54
	v_rcp_f32_e32 v55, v55
	v_mul_f32_e32 v44, v44, v52
	v_mul_f32_e32 v45, v45, v53
	v_mul_f32_e32 v46, v46, v54
	v_mul_f32_e32 v47, v47, v55
	v_mul_f32_e32 v44, v48, v44
	v_mul_f32_e32 v45, v49, v45
	v_mul_f32_e32 v46, v50, v46
	v_mul_f32_e32 v47, v51, v47
	v_mov_b32_e32 v124, v242
	v_mov_b32_e32 v125, v243
	v_cvt_pk_bf16_f32 v126, v44, v45
	v_cvt_pk_bf16_f32 v127, v46, v47
	v_mov_b32_e32 v58, v234
	s_mov_b64 s[8:9], exec
	s_and_b32 s39, s12, 7
	s_cmp_eq_u32 s39, 0
	s_cbranch_scc1 .Leu_g00_all
	s_cmp_lg_u32 s63, 0
	s_cbranch_scc1 .Leu_g00_all
	s_andn2_b64 exec, exec, s[14:15]
.Leu_g00_all:
	global_store_dwordx4 v58, v[124:127], s[16:17]
	s_mov_b64 exec, s[8:9]
	s_cmp_lg_u32 s63, 0
	s_cbranch_scc1 .Leu_halo_skip_a0n1
	v_mul_u32_u24_e32 v58, 0xb000, v56
	v_lshl_add_u32 v58, v57, 5, v58
	s_mul_i32 s39, s12, 0x2c000
	s_lshl_b32 s40, s13, 9
	s_add_i32 s39, s39, s40
	s_lshl_b32 s40, s64, 2
	s_add_i32 s39, s39, s40
	s_add_u32 s20, s72, s39
	s_addc_u32 s21, s73, 0
	s_add_u32 s22, s20, 0x5800
	s_addc_u32 s23, s21, 0
	s_and_saveexec_b64 s[8:9], s[14:15]
	global_store_dwordx4 v58, v[160:163], s[20:21] offset:16
	global_store_dwordx4 v58, v[156:159], s[22:23] offset:16
	s_mov_b64 exec, s[8:9]
.Leu_halo_skip_a0n1:
	v_fma_f32 v44, v180, v152, v188
	v_fma_f32 v45, v181, v153, v189
	v_fma_f32 v46, v182, v154, v190
	v_fma_f32 v47, v183, v155, v191
	v_fma_f32 v48, v172, v148, v168
	v_fma_f32 v49, v173, v149, v169
	v_fma_f32 v50, v174, v150, v170
	v_fma_f32 v51, v175, v151, v171
	v_fmac_f32_dpp v44, v152, v192 row_shr:1 row_mask:0xf bank_mask:0xf
	v_fmac_f32_dpp v45, v153, v193 row_shr:1 row_mask:0xf bank_mask:0xf
	v_fmac_f32_dpp v46, v154, v194 row_shr:1 row_mask:0xf bank_mask:0xf
	v_fmac_f32_dpp v47, v155, v195 row_shr:1 row_mask:0xf bank_mask:0xf
	v_fmac_f32_dpp v48, v148, v176 row_shr:1 row_mask:0xf bank_mask:0xf
	v_fmac_f32_dpp v49, v149, v177 row_shr:1 row_mask:0xf bank_mask:0xf
	v_fmac_f32_dpp v50, v150, v178 row_shr:1 row_mask:0xf bank_mask:0xf
	v_fmac_f32_dpp v51, v151, v179 row_shr:1 row_mask:0xf bank_mask:0xf
	v_fmac_f32_dpp v44, v152, v236 row_shr:2 row_mask:0xf bank_mask:0xf
	v_fmac_f32_dpp v45, v153, v237 row_shr:2 row_mask:0xf bank_mask:0xf
	v_fmac_f32_dpp v46, v154, v238 row_shr:2 row_mask:0xf bank_mask:0xf
	v_fmac_f32_dpp v47, v155, v239 row_shr:2 row_mask:0xf bank_mask:0xf
	v_fmac_f32_dpp v48, v148, v184 row_shr:2 row_mask:0xf bank_mask:0xf
	v_fmac_f32_dpp v49, v149, v185 row_shr:2 row_mask:0xf bank_mask:0xf
	v_fmac_f32_dpp v50, v150, v186 row_shr:2 row_mask:0xf bank_mask:0xf
	v_fmac_f32_dpp v51, v151, v187 row_shr:2 row_mask:0xf bank_mask:0xf
	v_fmac_f32_dpp v44, v160, v28 row_ror:1 row_mask:0xf bank_mask:0xf
	v_fmac_f32_dpp v45, v161, v29 row_ror:1 row_mask:0xf bank_mask:0xf
	v_fmac_f32_dpp v46, v162, v30 row_ror:1 row_mask:0xf bank_mask:0xf
	v_fmac_f32_dpp v47, v163, v31 row_ror:1 row_mask:0xf bank_mask:0xf
	v_fmac_f32_dpp v48, v156, v36 row_ror:1 row_mask:0xf bank_mask:0xf
	v_fmac_f32_dpp v49, v157, v37 row_ror:1 row_mask:0xf bank_mask:0xf
	v_fmac_f32_dpp v50, v158, v38 row_ror:1 row_mask:0xf bank_mask:0xf
	v_fmac_f32_dpp v51, v159, v39 row_ror:1 row_mask:0xf bank_mask:0xf
	v_fmac_f32_dpp v44, v160, v32 row_ror:2 row_mask:0xf bank_mask:0xf
	v_fmac_f32_dpp v45, v161, v33 row_ror:2 row_mask:0xf bank_mask:0xf
	v_fmac_f32_dpp v46, v162, v34 row_ror:2 row_mask:0xf bank_mask:0xf
	v_fmac_f32_dpp v47, v163, v35 row_ror:2 row_mask:0xf bank_mask:0xf
	v_fmac_f32_dpp v48, v156, v40 row_ror:2 row_mask:0xf bank_mask:0xf
	v_fmac_f32_dpp v49, v157, v41 row_ror:2 row_mask:0xf bank_mask:0xf
	v_fmac_f32_dpp v50, v158, v42 row_ror:2 row_mask:0xf bank_mask:0xf
	v_fmac_f32_dpp v51, v159, v43 row_ror:2 row_mask:0xf bank_mask:0xf
	v_mul_f32_e32 v52, s41, v44
	v_mul_f32_e32 v53, s41, v45
	v_mul_f32_e32 v54, s41, v46
	v_mul_f32_e32 v55, s41, v47
	v_exp_f32_e32 v52, v52
	v_exp_f32_e32 v53, v53
	v_exp_f32_e32 v54, v54
	v_exp_f32_e32 v55, v55
	v_add_f32_e32 v52, 1.0, v52
	v_add_f32_e32 v53, 1.0, v53
	v_add_f32_e32 v54, 1.0, v54
	v_add_f32_e32 v55, 1.0, v55
	v_rcp_f32_e32 v52, v52
	v_rcp_f32_e32 v53, v53
	v_rcp_f32_e32 v54, v54
	v_rcp_f32_e32 v55, v55
	v_mul_f32_e32 v44, v44, v52
	v_mul_f32_e32 v45, v45, v53
	v_mul_f32_e32 v46, v46, v54
	v_mul_f32_e32 v47, v47, v55
	v_mul_f32_e32 v44, v48, v44
	v_mul_f32_e32 v45, v49, v45
	v_mul_f32_e32 v46, v50, v46
	v_mul_f32_e32 v47, v51, v47
	v_mov_b32_e32 v88, v244
	v_mov_b32_e32 v89, v245
	v_cvt_pk_bf16_f32 v90, v44, v45
	v_cvt_pk_bf16_f32 v91, v46, v47
	v_add_u32_e32 v58, 0x2c000, v234
	global_store_dwordx4 v58, v[88:91], s[16:17]
	v_fma_f32 v44, v180, v144, v188
	v_fma_f32 v45, v181, v145, v189
	v_fma_f32 v46, v182, v146, v190
	v_fma_f32 v47, v183, v147, v191
	v_fma_f32 v48, v172, v140, v168
	v_fma_f32 v49, v173, v141, v169
	v_fma_f32 v50, v174, v142, v170
	v_fma_f32 v51, v175, v143, v171
	v_fmac_f32_dpp v44, v144, v192 row_shr:1 row_mask:0xf bank_mask:0xf
	v_fmac_f32_dpp v45, v145, v193 row_shr:1 row_mask:0xf bank_mask:0xf
	v_fmac_f32_dpp v46, v146, v194 row_shr:1 row_mask:0xf bank_mask:0xf
	v_fmac_f32_dpp v47, v147, v195 row_shr:1 row_mask:0xf bank_mask:0xf
	v_fmac_f32_dpp v48, v140, v176 row_shr:1 row_mask:0xf bank_mask:0xf
	v_fmac_f32_dpp v49, v141, v177 row_shr:1 row_mask:0xf bank_mask:0xf
	v_fmac_f32_dpp v50, v142, v178 row_shr:1 row_mask:0xf bank_mask:0xf
	v_fmac_f32_dpp v51, v143, v179 row_shr:1 row_mask:0xf bank_mask:0xf
	v_fmac_f32_dpp v44, v144, v236 row_shr:2 row_mask:0xf bank_mask:0xf
	v_fmac_f32_dpp v45, v145, v237 row_shr:2 row_mask:0xf bank_mask:0xf
	v_fmac_f32_dpp v46, v146, v238 row_shr:2 row_mask:0xf bank_mask:0xf
	v_fmac_f32_dpp v47, v147, v239 row_shr:2 row_mask:0xf bank_mask:0xf
	v_fmac_f32_dpp v48, v140, v184 row_shr:2 row_mask:0xf bank_mask:0xf
	v_fmac_f32_dpp v49, v141, v185 row_shr:2 row_mask:0xf bank_mask:0xf
	v_fmac_f32_dpp v50, v142, v186 row_shr:2 row_mask:0xf bank_mask:0xf
	v_fmac_f32_dpp v51, v143, v187 row_shr:2 row_mask:0xf bank_mask:0xf
	v_fmac_f32_dpp v44, v152, v28 row_ror:1 row_mask:0xf bank_mask:0xf
	v_fmac_f32_dpp v45, v153, v29 row_ror:1 row_mask:0xf bank_mask:0xf
	v_fmac_f32_dpp v46, v154, v30 row_ror:1 row_mask:0xf bank_mask:0xf
	v_fmac_f32_dpp v47, v155, v31 row_ror:1 row_mask:0xf bank_mask:0xf
	v_fmac_f32_dpp v48, v148, v36 row_ror:1 row_mask:0xf bank_mask:0xf
	v_fmac_f32_dpp v49, v149, v37 row_ror:1 row_mask:0xf bank_mask:0xf
	v_fmac_f32_dpp v50, v150, v38 row_ror:1 row_mask:0xf bank_mask:0xf
	v_fmac_f32_dpp v51, v151, v39 row_ror:1 row_mask:0xf bank_mask:0xf
	v_fmac_f32_dpp v44, v152, v32 row_ror:2 row_mask:0xf bank_mask:0xf
	v_fmac_f32_dpp v45, v153, v33 row_ror:2 row_mask:0xf bank_mask:0xf
	v_fmac_f32_dpp v46, v154, v34 row_ror:2 row_mask:0xf bank_mask:0xf
	v_fmac_f32_dpp v47, v155, v35 row_ror:2 row_mask:0xf bank_mask:0xf
	v_fmac_f32_dpp v48, v148, v40 row_ror:2 row_mask:0xf bank_mask:0xf
	v_fmac_f32_dpp v49, v149, v41 row_ror:2 row_mask:0xf bank_mask:0xf
	v_fmac_f32_dpp v50, v150, v42 row_ror:2 row_mask:0xf bank_mask:0xf
	v_fmac_f32_dpp v51, v151, v43 row_ror:2 row_mask:0xf bank_mask:0xf
	v_mul_f32_e32 v52, s41, v44
	v_mul_f32_e32 v53, s41, v45
	v_mul_f32_e32 v54, s41, v46
	v_mul_f32_e32 v55, s41, v47
	v_exp_f32_e32 v52, v52
	v_exp_f32_e32 v53, v53
	v_exp_f32_e32 v54, v54
	v_exp_f32_e32 v55, v55
	v_add_f32_e32 v52, 1.0, v52
	v_add_f32_e32 v53, 1.0, v53
	v_add_f32_e32 v54, 1.0, v54
	v_add_f32_e32 v55, 1.0, v55
	v_rcp_f32_e32 v52, v52
	v_rcp_f32_e32 v53, v53
	v_rcp_f32_e32 v54, v54
	v_rcp_f32_e32 v55, v55
	v_mul_f32_e32 v44, v44, v52
	v_mul_f32_e32 v45, v45, v53
	v_mul_f32_e32 v46, v46, v54
	v_mul_f32_e32 v47, v47, v55
	v_mul_f32_e32 v44, v48, v44
	v_mul_f32_e32 v45, v49, v45
	v_mul_f32_e32 v46, v50, v46
	v_mul_f32_e32 v47, v51, v47
	v_mov_b32_e32 v124, v246
	v_mov_b32_e32 v125, v247
	v_cvt_pk_bf16_f32 v126, v44, v45
	v_cvt_pk_bf16_f32 v127, v46, v47
	v_add_u32_e32 v58, 0x58000, v234
	global_store_dwordx4 v58, v[124:127], s[16:17]
	v_fma_f32 v44, v180, v136, v188
	v_fma_f32 v45, v181, v137, v189
	v_fma_f32 v46, v182, v138, v190
	v_fma_f32 v47, v183, v139, v191
	v_fma_f32 v48, v172, v132, v168
	v_fma_f32 v49, v173, v133, v169
	v_fma_f32 v50, v174, v134, v170
	v_fma_f32 v51, v175, v135, v171
	v_fmac_f32_dpp v44, v136, v192 row_shr:1 row_mask:0xf bank_mask:0xf
	v_fmac_f32_dpp v45, v137, v193 row_shr:1 row_mask:0xf bank_mask:0xf
	v_fmac_f32_dpp v46, v138, v194 row_shr:1 row_mask:0xf bank_mask:0xf
	v_fmac_f32_dpp v47, v139, v195 row_shr:1 row_mask:0xf bank_mask:0xf
	v_fmac_f32_dpp v48, v132, v176 row_shr:1 row_mask:0xf bank_mask:0xf
	v_fmac_f32_dpp v49, v133, v177 row_shr:1 row_mask:0xf bank_mask:0xf
	v_fmac_f32_dpp v50, v134, v178 row_shr:1 row_mask:0xf bank_mask:0xf
	v_fmac_f32_dpp v51, v135, v179 row_shr:1 row_mask:0xf bank_mask:0xf
	v_fmac_f32_dpp v44, v136, v236 row_shr:2 row_mask:0xf bank_mask:0xf
	v_fmac_f32_dpp v45, v137, v237 row_shr:2 row_mask:0xf bank_mask:0xf
	v_fmac_f32_dpp v46, v138, v238 row_shr:2 row_mask:0xf bank_mask:0xf
	v_fmac_f32_dpp v47, v139, v239 row_shr:2 row_mask:0xf bank_mask:0xf
	v_fmac_f32_dpp v48, v132, v184 row_shr:2 row_mask:0xf bank_mask:0xf
	v_fmac_f32_dpp v49, v133, v185 row_shr:2 row_mask:0xf bank_mask:0xf
	v_fmac_f32_dpp v50, v134, v186 row_shr:2 row_mask:0xf bank_mask:0xf
	v_fmac_f32_dpp v51, v135, v187 row_shr:2 row_mask:0xf bank_mask:0xf
	v_fmac_f32_dpp v44, v144, v28 row_ror:1 row_mask:0xf bank_mask:0xf
	v_fmac_f32_dpp v45, v145, v29 row_ror:1 row_mask:0xf bank_mask:0xf
	v_fmac_f32_dpp v46, v146, v30 row_ror:1 row_mask:0xf bank_mask:0xf
	v_fmac_f32_dpp v47, v147, v31 row_ror:1 row_mask:0xf bank_mask:0xf
	v_fmac_f32_dpp v48, v140, v36 row_ror:1 row_mask:0xf bank_mask:0xf
	v_fmac_f32_dpp v49, v141, v37 row_ror:1 row_mask:0xf bank_mask:0xf
	v_fmac_f32_dpp v50, v142, v38 row_ror:1 row_mask:0xf bank_mask:0xf
	v_fmac_f32_dpp v51, v143, v39 row_ror:1 row_mask:0xf bank_mask:0xf
	v_fmac_f32_dpp v44, v144, v32 row_ror:2 row_mask:0xf bank_mask:0xf
	v_fmac_f32_dpp v45, v145, v33 row_ror:2 row_mask:0xf bank_mask:0xf
	v_fmac_f32_dpp v46, v146, v34 row_ror:2 row_mask:0xf bank_mask:0xf
	v_fmac_f32_dpp v47, v147, v35 row_ror:2 row_mask:0xf bank_mask:0xf
	v_fmac_f32_dpp v48, v140, v40 row_ror:2 row_mask:0xf bank_mask:0xf
	v_fmac_f32_dpp v49, v141, v41 row_ror:2 row_mask:0xf bank_mask:0xf
	v_fmac_f32_dpp v50, v142, v42 row_ror:2 row_mask:0xf bank_mask:0xf
	v_fmac_f32_dpp v51, v143, v43 row_ror:2 row_mask:0xf bank_mask:0xf
	v_mul_f32_e32 v52, s41, v44
	v_mul_f32_e32 v53, s41, v45
	v_mul_f32_e32 v54, s41, v46
	v_mul_f32_e32 v55, s41, v47
	v_exp_f32_e32 v52, v52
	v_exp_f32_e32 v53, v53
	v_exp_f32_e32 v54, v54
	v_exp_f32_e32 v55, v55
	v_add_f32_e32 v52, 1.0, v52
	v_add_f32_e32 v53, 1.0, v53
	v_add_f32_e32 v54, 1.0, v54
	v_add_f32_e32 v55, 1.0, v55
	v_rcp_f32_e32 v52, v52
	v_rcp_f32_e32 v53, v53
	v_rcp_f32_e32 v54, v54
	v_rcp_f32_e32 v55, v55
	v_mul_f32_e32 v44, v44, v52
	v_mul_f32_e32 v45, v45, v53
	v_mul_f32_e32 v46, v46, v54
	v_mul_f32_e32 v47, v47, v55
	v_mul_f32_e32 v44, v48, v44
	v_mul_f32_e32 v45, v49, v45
	v_mul_f32_e32 v46, v50, v46
	v_mul_f32_e32 v47, v51, v47
	v_mov_b32_e32 v88, v248
	v_mov_b32_e32 v89, v249
	v_cvt_pk_bf16_f32 v90, v44, v45
	v_cvt_pk_bf16_f32 v91, v46, v47
	v_add_u32_e32 v58, 0x84000, v234
	global_store_dwordx4 v58, v[88:91], s[16:17]
	v_fma_f32 v44, v180, v64, v188
	v_fma_f32 v45, v181, v65, v189
	v_fma_f32 v46, v182, v66, v190
	v_fma_f32 v47, v183, v67, v191
	v_fma_f32 v48, v172, v60, v168
	v_fma_f32 v49, v173, v61, v169
	v_fma_f32 v50, v174, v62, v170
	v_fma_f32 v51, v175, v63, v171
	v_fmac_f32_dpp v44, v64, v192 row_shr:1 row_mask:0xf bank_mask:0xf
	v_fmac_f32_dpp v45, v65, v193 row_shr:1 row_mask:0xf bank_mask:0xf
	v_fmac_f32_dpp v46, v66, v194 row_shr:1 row_mask:0xf bank_mask:0xf
	v_fmac_f32_dpp v47, v67, v195 row_shr:1 row_mask:0xf bank_mask:0xf
	v_fmac_f32_dpp v48, v60, v176 row_shr:1 row_mask:0xf bank_mask:0xf
	v_fmac_f32_dpp v49, v61, v177 row_shr:1 row_mask:0xf bank_mask:0xf
	v_fmac_f32_dpp v50, v62, v178 row_shr:1 row_mask:0xf bank_mask:0xf
	v_fmac_f32_dpp v51, v63, v179 row_shr:1 row_mask:0xf bank_mask:0xf
	v_fmac_f32_dpp v44, v64, v236 row_shr:2 row_mask:0xf bank_mask:0xf
	v_fmac_f32_dpp v45, v65, v237 row_shr:2 row_mask:0xf bank_mask:0xf
	v_fmac_f32_dpp v46, v66, v238 row_shr:2 row_mask:0xf bank_mask:0xf
	v_fmac_f32_dpp v47, v67, v239 row_shr:2 row_mask:0xf bank_mask:0xf
	v_fmac_f32_dpp v48, v60, v184 row_shr:2 row_mask:0xf bank_mask:0xf
	v_fmac_f32_dpp v49, v61, v185 row_shr:2 row_mask:0xf bank_mask:0xf
	v_fmac_f32_dpp v50, v62, v186 row_shr:2 row_mask:0xf bank_mask:0xf
	v_fmac_f32_dpp v51, v63, v187 row_shr:2 row_mask:0xf bank_mask:0xf
	v_fmac_f32_dpp v44, v204, v28 row_ror:1 row_mask:0xf bank_mask:0xf
	v_fmac_f32_dpp v45, v205, v29 row_ror:1 row_mask:0xf bank_mask:0xf
	v_fmac_f32_dpp v46, v206, v30 row_ror:1 row_mask:0xf bank_mask:0xf
	v_fmac_f32_dpp v47, v207, v31 row_ror:1 row_mask:0xf bank_mask:0xf
	v_fmac_f32_dpp v48, v208, v36 row_ror:1 row_mask:0xf bank_mask:0xf
	v_fmac_f32_dpp v49, v209, v37 row_ror:1 row_mask:0xf bank_mask:0xf
	v_fmac_f32_dpp v50, v210, v38 row_ror:1 row_mask:0xf bank_mask:0xf
	v_fmac_f32_dpp v51, v211, v39 row_ror:1 row_mask:0xf bank_mask:0xf
	v_fmac_f32_dpp v44, v204, v32 row_ror:2 row_mask:0xf bank_mask:0xf
	v_fmac_f32_dpp v45, v205, v33 row_ror:2 row_mask:0xf bank_mask:0xf
	v_fmac_f32_dpp v46, v206, v34 row_ror:2 row_mask:0xf bank_mask:0xf
	v_fmac_f32_dpp v47, v207, v35 row_ror:2 row_mask:0xf bank_mask:0xf
	v_fmac_f32_dpp v48, v208, v40 row_ror:2 row_mask:0xf bank_mask:0xf
	v_fmac_f32_dpp v49, v209, v41 row_ror:2 row_mask:0xf bank_mask:0xf
	v_fmac_f32_dpp v50, v210, v42 row_ror:2 row_mask:0xf bank_mask:0xf
	v_fmac_f32_dpp v51, v211, v43 row_ror:2 row_mask:0xf bank_mask:0xf
	v_mul_f32_e32 v52, s41, v44
	v_mul_f32_e32 v53, s41, v45
	v_mul_f32_e32 v54, s41, v46
	v_mul_f32_e32 v55, s41, v47
	v_exp_f32_e32 v52, v52
	v_exp_f32_e32 v53, v53
	v_exp_f32_e32 v54, v54
	v_exp_f32_e32 v55, v55
	v_add_f32_e32 v52, 1.0, v52
	v_add_f32_e32 v53, 1.0, v53
	v_add_f32_e32 v54, 1.0, v54
	v_add_f32_e32 v55, 1.0, v55
	v_rcp_f32_e32 v52, v52
	v_rcp_f32_e32 v53, v53
	v_rcp_f32_e32 v54, v54
	v_rcp_f32_e32 v55, v55
	v_mul_f32_e32 v44, v44, v52
	v_mul_f32_e32 v45, v45, v53
	v_mul_f32_e32 v46, v46, v54
	v_mul_f32_e32 v47, v47, v55
	v_mul_f32_e32 v44, v48, v44
	v_mul_f32_e32 v45, v49, v45
	v_mul_f32_e32 v46, v50, v46
	v_mul_f32_e32 v47, v51, v47
	v_mov_b32_e32 v124, v164
	v_mov_b32_e32 v125, v165
	v_cvt_pk_bf16_f32 v126, v44, v45
	v_cvt_pk_bf16_f32 v127, v46, v47
	v_mov_b32_e32 v58, v234
	global_store_dwordx4 v58, v[124:127], s[18:19]
	v_fma_f32 v44, v180, v24, v188
	v_fma_f32 v45, v181, v25, v189
	v_fma_f32 v46, v182, v26, v190
	v_fma_f32 v47, v183, v27, v191
	v_fma_f32 v48, v172, v20, v168
	v_fma_f32 v49, v173, v21, v169
	v_fma_f32 v50, v174, v22, v170
	v_fma_f32 v51, v175, v23, v171
	v_fmac_f32_dpp v44, v24, v192 row_shr:1 row_mask:0xf bank_mask:0xf
	v_fmac_f32_dpp v45, v25, v193 row_shr:1 row_mask:0xf bank_mask:0xf
	v_fmac_f32_dpp v46, v26, v194 row_shr:1 row_mask:0xf bank_mask:0xf
	v_fmac_f32_dpp v47, v27, v195 row_shr:1 row_mask:0xf bank_mask:0xf
	v_fmac_f32_dpp v48, v20, v176 row_shr:1 row_mask:0xf bank_mask:0xf
	v_fmac_f32_dpp v49, v21, v177 row_shr:1 row_mask:0xf bank_mask:0xf
	v_fmac_f32_dpp v50, v22, v178 row_shr:1 row_mask:0xf bank_mask:0xf
	v_fmac_f32_dpp v51, v23, v179 row_shr:1 row_mask:0xf bank_mask:0xf
	v_fmac_f32_dpp v44, v24, v236 row_shr:2 row_mask:0xf bank_mask:0xf
	v_fmac_f32_dpp v45, v25, v237 row_shr:2 row_mask:0xf bank_mask:0xf
	v_fmac_f32_dpp v46, v26, v238 row_shr:2 row_mask:0xf bank_mask:0xf
	v_fmac_f32_dpp v47, v27, v239 row_shr:2 row_mask:0xf bank_mask:0xf
	v_fmac_f32_dpp v48, v20, v184 row_shr:2 row_mask:0xf bank_mask:0xf
	v_fmac_f32_dpp v49, v21, v185 row_shr:2 row_mask:0xf bank_mask:0xf
	v_fmac_f32_dpp v50, v22, v186 row_shr:2 row_mask:0xf bank_mask:0xf
	v_fmac_f32_dpp v51, v23, v187 row_shr:2 row_mask:0xf bank_mask:0xf
	v_fmac_f32_dpp v44, v64, v28 row_ror:1 row_mask:0xf bank_mask:0xf
	v_fmac_f32_dpp v45, v65, v29 row_ror:1 row_mask:0xf bank_mask:0xf
	v_fmac_f32_dpp v46, v66, v30 row_ror:1 row_mask:0xf bank_mask:0xf
	v_fmac_f32_dpp v47, v67, v31 row_ror:1 row_mask:0xf bank_mask:0xf
	v_fmac_f32_dpp v48, v60, v36 row_ror:1 row_mask:0xf bank_mask:0xf
	v_fmac_f32_dpp v49, v61, v37 row_ror:1 row_mask:0xf bank_mask:0xf
	v_fmac_f32_dpp v50, v62, v38 row_ror:1 row_mask:0xf bank_mask:0xf
	v_fmac_f32_dpp v51, v63, v39 row_ror:1 row_mask:0xf bank_mask:0xf
	v_fmac_f32_dpp v44, v64, v32 row_ror:2 row_mask:0xf bank_mask:0xf
	v_fmac_f32_dpp v45, v65, v33 row_ror:2 row_mask:0xf bank_mask:0xf
	v_fmac_f32_dpp v46, v66, v34 row_ror:2 row_mask:0xf bank_mask:0xf
	v_fmac_f32_dpp v47, v67, v35 row_ror:2 row_mask:0xf bank_mask:0xf
	v_fmac_f32_dpp v48, v60, v40 row_ror:2 row_mask:0xf bank_mask:0xf
	v_fmac_f32_dpp v49, v61, v41 row_ror:2 row_mask:0xf bank_mask:0xf
	v_fmac_f32_dpp v50, v62, v42 row_ror:2 row_mask:0xf bank_mask:0xf
	v_fmac_f32_dpp v51, v63, v43 row_ror:2 row_mask:0xf bank_mask:0xf
	v_mul_f32_e32 v52, s41, v44
	v_mul_f32_e32 v53, s41, v45
	v_mul_f32_e32 v54, s41, v46
	v_mul_f32_e32 v55, s41, v47
	v_exp_f32_e32 v52, v52
	v_exp_f32_e32 v53, v53
	v_exp_f32_e32 v54, v54
	v_exp_f32_e32 v55, v55
	v_add_f32_e32 v52, 1.0, v52
	v_add_f32_e32 v53, 1.0, v53
	v_add_f32_e32 v54, 1.0, v54
	v_add_f32_e32 v55, 1.0, v55
	v_rcp_f32_e32 v52, v52
	v_rcp_f32_e32 v53, v53
	v_rcp_f32_e32 v54, v54
	v_rcp_f32_e32 v55, v55
	v_mul_f32_e32 v44, v44, v52
	v_mul_f32_e32 v45, v45, v53
	v_mul_f32_e32 v46, v46, v54
	v_mul_f32_e32 v47, v47, v55
	v_mul_f32_e32 v44, v48, v44
	v_mul_f32_e32 v45, v49, v45
	v_mul_f32_e32 v46, v50, v46
	v_mul_f32_e32 v47, v51, v47
	v_mov_b32_e32 v88, v166
	v_mov_b32_e32 v89, v167
	v_cvt_pk_bf16_f32 v90, v44, v45
	v_cvt_pk_bf16_f32 v91, v46, v47
	v_add_u32_e32 v58, 0x2c000, v234
	global_store_dwordx4 v58, v[88:91], s[18:19]
	v_fma_f32 v44, v180, v16, v188
	v_fma_f32 v45, v181, v17, v189
	v_fma_f32 v46, v182, v18, v190
	v_fma_f32 v47, v183, v19, v191
	v_fma_f32 v48, v172, v12, v168
	v_fma_f32 v49, v173, v13, v169
	v_fma_f32 v50, v174, v14, v170
	v_fma_f32 v51, v175, v15, v171
	v_fmac_f32_dpp v44, v16, v192 row_shr:1 row_mask:0xf bank_mask:0xf
	v_fmac_f32_dpp v45, v17, v193 row_shr:1 row_mask:0xf bank_mask:0xf
	v_fmac_f32_dpp v46, v18, v194 row_shr:1 row_mask:0xf bank_mask:0xf
	v_fmac_f32_dpp v47, v19, v195 row_shr:1 row_mask:0xf bank_mask:0xf
	v_fmac_f32_dpp v48, v12, v176 row_shr:1 row_mask:0xf bank_mask:0xf
	v_fmac_f32_dpp v49, v13, v177 row_shr:1 row_mask:0xf bank_mask:0xf
	v_fmac_f32_dpp v50, v14, v178 row_shr:1 row_mask:0xf bank_mask:0xf
	v_fmac_f32_dpp v51, v15, v179 row_shr:1 row_mask:0xf bank_mask:0xf
	v_fmac_f32_dpp v44, v16, v236 row_shr:2 row_mask:0xf bank_mask:0xf
	v_fmac_f32_dpp v45, v17, v237 row_shr:2 row_mask:0xf bank_mask:0xf
	v_fmac_f32_dpp v46, v18, v238 row_shr:2 row_mask:0xf bank_mask:0xf
	v_fmac_f32_dpp v47, v19, v239 row_shr:2 row_mask:0xf bank_mask:0xf
	v_fmac_f32_dpp v48, v12, v184 row_shr:2 row_mask:0xf bank_mask:0xf
	v_fmac_f32_dpp v49, v13, v185 row_shr:2 row_mask:0xf bank_mask:0xf
	v_fmac_f32_dpp v50, v14, v186 row_shr:2 row_mask:0xf bank_mask:0xf
	v_fmac_f32_dpp v51, v15, v187 row_shr:2 row_mask:0xf bank_mask:0xf
	v_fmac_f32_dpp v44, v24, v28 row_ror:1 row_mask:0xf bank_mask:0xf
	v_fmac_f32_dpp v45, v25, v29 row_ror:1 row_mask:0xf bank_mask:0xf
	v_fmac_f32_dpp v46, v26, v30 row_ror:1 row_mask:0xf bank_mask:0xf
	v_fmac_f32_dpp v47, v27, v31 row_ror:1 row_mask:0xf bank_mask:0xf
	v_fmac_f32_dpp v48, v20, v36 row_ror:1 row_mask:0xf bank_mask:0xf
	v_fmac_f32_dpp v49, v21, v37 row_ror:1 row_mask:0xf bank_mask:0xf
	v_fmac_f32_dpp v50, v22, v38 row_ror:1 row_mask:0xf bank_mask:0xf
	v_fmac_f32_dpp v51, v23, v39 row_ror:1 row_mask:0xf bank_mask:0xf
	v_fmac_f32_dpp v44, v24, v32 row_ror:2 row_mask:0xf bank_mask:0xf
	v_fmac_f32_dpp v45, v25, v33 row_ror:2 row_mask:0xf bank_mask:0xf
	v_fmac_f32_dpp v46, v26, v34 row_ror:2 row_mask:0xf bank_mask:0xf
	v_fmac_f32_dpp v47, v27, v35 row_ror:2 row_mask:0xf bank_mask:0xf
	v_fmac_f32_dpp v48, v20, v40 row_ror:2 row_mask:0xf bank_mask:0xf
	v_fmac_f32_dpp v49, v21, v41 row_ror:2 row_mask:0xf bank_mask:0xf
	v_fmac_f32_dpp v50, v22, v42 row_ror:2 row_mask:0xf bank_mask:0xf
	v_fmac_f32_dpp v51, v23, v43 row_ror:2 row_mask:0xf bank_mask:0xf
	v_mul_f32_e32 v52, s41, v44
	v_mul_f32_e32 v53, s41, v45
	v_mul_f32_e32 v54, s41, v46
	v_mul_f32_e32 v55, s41, v47
	v_exp_f32_e32 v52, v52
	v_exp_f32_e32 v53, v53
	v_exp_f32_e32 v54, v54
	v_exp_f32_e32 v55, v55
	v_add_f32_e32 v52, 1.0, v52
	v_add_f32_e32 v53, 1.0, v53
	v_add_f32_e32 v54, 1.0, v54
	v_add_f32_e32 v55, 1.0, v55
	v_rcp_f32_e32 v52, v52
	v_rcp_f32_e32 v53, v53
	v_rcp_f32_e32 v54, v54
	v_rcp_f32_e32 v55, v55
	v_mul_f32_e32 v44, v44, v52
	v_mul_f32_e32 v45, v45, v53
	v_mul_f32_e32 v46, v46, v54
	v_mul_f32_e32 v47, v47, v55
	v_mul_f32_e32 v44, v48, v44
	v_mul_f32_e32 v45, v49, v45
	v_mul_f32_e32 v46, v50, v46
	v_mul_f32_e32 v47, v51, v47
	v_mov_b32_e32 v124, v128
	v_mov_b32_e32 v125, v129
	v_cvt_pk_bf16_f32 v126, v44, v45
	v_cvt_pk_bf16_f32 v127, v46, v47
	v_add_u32_e32 v58, 0x58000, v234
	global_store_dwordx4 v58, v[124:127], s[18:19]
	v_fma_f32 v44, v180, v8, v188
	v_fma_f32 v45, v181, v9, v189
	v_fma_f32 v46, v182, v10, v190
	v_fma_f32 v47, v183, v11, v191
	v_fma_f32 v48, v172, v4, v168
	v_fma_f32 v49, v173, v5, v169
	v_fma_f32 v50, v174, v6, v170
	v_fma_f32 v51, v175, v7, v171
	v_fmac_f32_dpp v44, v8, v192 row_shr:1 row_mask:0xf bank_mask:0xf
	v_fmac_f32_dpp v45, v9, v193 row_shr:1 row_mask:0xf bank_mask:0xf
	v_fmac_f32_dpp v46, v10, v194 row_shr:1 row_mask:0xf bank_mask:0xf
	v_fmac_f32_dpp v47, v11, v195 row_shr:1 row_mask:0xf bank_mask:0xf
	v_fmac_f32_dpp v48, v4, v176 row_shr:1 row_mask:0xf bank_mask:0xf
	v_fmac_f32_dpp v49, v5, v177 row_shr:1 row_mask:0xf bank_mask:0xf
	v_fmac_f32_dpp v50, v6, v178 row_shr:1 row_mask:0xf bank_mask:0xf
	v_fmac_f32_dpp v51, v7, v179 row_shr:1 row_mask:0xf bank_mask:0xf
	v_fmac_f32_dpp v44, v8, v236 row_shr:2 row_mask:0xf bank_mask:0xf
	v_fmac_f32_dpp v45, v9, v237 row_shr:2 row_mask:0xf bank_mask:0xf
	v_fmac_f32_dpp v46, v10, v238 row_shr:2 row_mask:0xf bank_mask:0xf
	v_fmac_f32_dpp v47, v11, v239 row_shr:2 row_mask:0xf bank_mask:0xf
	v_fmac_f32_dpp v48, v4, v184 row_shr:2 row_mask:0xf bank_mask:0xf
	v_fmac_f32_dpp v49, v5, v185 row_shr:2 row_mask:0xf bank_mask:0xf
	v_fmac_f32_dpp v50, v6, v186 row_shr:2 row_mask:0xf bank_mask:0xf
	v_fmac_f32_dpp v51, v7, v187 row_shr:2 row_mask:0xf bank_mask:0xf
	v_fmac_f32_dpp v44, v16, v28 row_ror:1 row_mask:0xf bank_mask:0xf
	v_fmac_f32_dpp v45, v17, v29 row_ror:1 row_mask:0xf bank_mask:0xf
	v_fmac_f32_dpp v46, v18, v30 row_ror:1 row_mask:0xf bank_mask:0xf
	v_fmac_f32_dpp v47, v19, v31 row_ror:1 row_mask:0xf bank_mask:0xf
	v_fmac_f32_dpp v48, v12, v36 row_ror:1 row_mask:0xf bank_mask:0xf
	v_fmac_f32_dpp v49, v13, v37 row_ror:1 row_mask:0xf bank_mask:0xf
	v_fmac_f32_dpp v50, v14, v38 row_ror:1 row_mask:0xf bank_mask:0xf
	v_fmac_f32_dpp v51, v15, v39 row_ror:1 row_mask:0xf bank_mask:0xf
	v_fmac_f32_dpp v44, v16, v32 row_ror:2 row_mask:0xf bank_mask:0xf
	v_fmac_f32_dpp v45, v17, v33 row_ror:2 row_mask:0xf bank_mask:0xf
	v_fmac_f32_dpp v46, v18, v34 row_ror:2 row_mask:0xf bank_mask:0xf
	v_fmac_f32_dpp v47, v19, v35 row_ror:2 row_mask:0xf bank_mask:0xf
	v_fmac_f32_dpp v48, v12, v40 row_ror:2 row_mask:0xf bank_mask:0xf
	v_fmac_f32_dpp v49, v13, v41 row_ror:2 row_mask:0xf bank_mask:0xf
	v_fmac_f32_dpp v50, v14, v42 row_ror:2 row_mask:0xf bank_mask:0xf
	v_fmac_f32_dpp v51, v15, v43 row_ror:2 row_mask:0xf bank_mask:0xf
	v_mul_f32_e32 v52, s41, v44
	v_mul_f32_e32 v53, s41, v45
	v_mul_f32_e32 v54, s41, v46
	v_mul_f32_e32 v55, s41, v47
	v_exp_f32_e32 v52, v52
	v_exp_f32_e32 v53, v53
	v_exp_f32_e32 v54, v54
	v_exp_f32_e32 v55, v55
	v_add_f32_e32 v52, 1.0, v52
	v_add_f32_e32 v53, 1.0, v53
	v_add_f32_e32 v54, 1.0, v54
	v_add_f32_e32 v55, 1.0, v55
	v_rcp_f32_e32 v52, v52
	v_rcp_f32_e32 v53, v53
	v_rcp_f32_e32 v54, v54
	v_rcp_f32_e32 v55, v55
	v_mul_f32_e32 v44, v44, v52
	v_mul_f32_e32 v45, v45, v53
	v_mul_f32_e32 v46, v46, v54
	v_mul_f32_e32 v47, v47, v55
	v_mul_f32_e32 v44, v48, v44
	v_mul_f32_e32 v45, v49, v45
	v_mul_f32_e32 v46, v50, v46
	v_mul_f32_e32 v47, v51, v47
	v_mov_b32_e32 v88, v130
	v_mov_b32_e32 v89, v131
	v_cvt_pk_bf16_f32 v90, v44, v45
	v_cvt_pk_bf16_f32 v91, v46, v47
	v_add_u32_e32 v58, 0x84000, v234
	global_store_dwordx4 v58, v[88:91], s[18:19]
	s_cmp_eq_u32 s63, 0
	s_cbranch_scc1 .Leu_halo_skip_a1n1
	v_subrev_u32_e32 v58, 12, v56
	v_mul_u32_u24_e32 v58, 0xb000, v58
	v_lshl_add_u32 v58, v57, 5, v58
	s_mul_i32 s39, s12, 0x2c000
	s_lshl_b32 s40, s13, 9
	s_add_i32 s39, s39, s40
	s_lshl_b32 s40, s64, 2
	s_add_i32 s39, s39, s40
	s_add_u32 s20, s72, s39
	s_addc_u32 s21, s73, 0
	s_add_u32 s22, s20, 0x5800
	s_addc_u32 s23, s21, 0
	s_and_saveexec_b64 s[8:9], s[10:11]
	global_store_dwordx4 v58, v[8:11], s[20:21] offset:16
	global_store_dwordx4 v58, v[4:7], s[22:23] offset:16
	s_and_b32 s39, s12, 7
	s_cmp_lg_u32 s39, 7
	s_cbranch_scc1 .Leu_ffn_skip_a1n1
	v_subrev_u32_e32 v59, 14, v56
	v_mul_u32_u24_e32 v59, 0xb000, v59
	v_lshl_add_u32 v59, v57, 5, v59
	s_lshr_b32 s39, s12, 3
	s_mul_i32 s39, s39, 0x16000
	s_lshl_b32 s40, s13, 9
	s_add_i32 s39, s39, s40
	s_lshl_b32 s40, s64, 2
	s_add_i32 s39, s39, s40
	s_add_u32 s20, s28, s39
	s_addc_u32 s21, s29, 0
	s_add_u32 s22, s20, 0x5800
	s_addc_u32 s23, s21, 0
	global_store_dwordx4 v59, v[8:11], s[20:21] offset:16
	global_store_dwordx4 v59, v[4:7], s[22:23] offset:16

.Leu_halo_skip_a1n1:
.LBB0_1413:
	s_or_b64 exec, exec, s[10:11]
	s_waitcnt lgkmcnt(0)
	s_andn2_b64 vcc, exec, s[6:7]
	s_mov_b64 s[6:7], -1
	s_barrier
	s_cbranch_vccnz .LBB0_1332
	s_andn2_b64 vcc, exec, s[26:27]
	s_cbranch_vccnz .LBB0_1331
	s_barrier
	s_branch .LBB0_1331
